# attnA-pingpong-v2: hand-written ping-pong diff-attention loop, K+V via LDS-DMA
# speedup vs baseline: 1.0543x; 1.0543x over previous
; #define SBAR() __builtin_amdgcn_sched_barrier(0)
; template <int MODE>
; __device__ __forceinline__ void attn_unit(const UnitArgs& A, char* lds, const int wave_) {
;     ...
;     float l_reg = 0; f32x16 o[4] = {}; bf16x8 qr[4];
;     { const bf16_t* Qw = A.Qb + (long)(qb * QBLK + r32) * NZ + half * 64 + hi * 8;
; #pragma unroll
;       for (int d0 = 0; d0 < 4; ++d0) qr[d0] = *reinterpret_cast<const bf16x8*>(Qw + d0 * 16); }
;     const int sr = tid >> 4, sc = (tid & 15) * 8, vst0 = v_st(sr, sc);
;     const int vbase = (int)(uintptr_t)V_lds + v_rd_base(lane) + (MODE == 0 ? 0 : half * 1024);
;     const int ldk = A.ldk; const unsigned ldoff = (unsigned)(sr * ldk + sc) * 2u;
;     struct { bf16x8 vs0, vs1; } sr_[1];
;     const unsigned kdoff = (unsigned)(sr * ldk + (((tid & 15) ^ (sr & 7)) * 8)) * 2u;
;     const unsigned kdst0 = (unsigned)__builtin_amdgcn_readfirstlane((int)((unsigned)(uintptr_t)K_lds + (unsigned)wid * 1024u));
;     ...
;     auto zone_of = [&](int t) -> int { const int k0 = 64 * t, qw0 = A.q0 + 32 * qb; return (k0 + 63 - qw0 <= -128) ? 0 : ((k0 - qw0 - 31 >= 128) ? 2 : 1); };
;     ...
;     auto post = [&](f32x16& p0, f32x16& p1, int t) {
;         SBAR();
;         if (MODE == 0) {
;             if (zone_of(t) == 1) { const int k0 = 64 * t, qw0 = A.q0 + 32 * qb;
;                 const float* b = lutA + A.h * LUTA_STRIDE + (k0 - qw0 - r32 + 4 * hi + 320);
; #pragma unroll
;                 for (int r = 0; r < 16; ++r) { const int c = (r & 3) + 8 * (r >> 2); p0[r] += b[c]; p1[r] += b[32 + c]; } }
;         } else if (MODE == 1) {
;             const int kr = A.tile0 + t, rq = A.q0 + (qb >> 1);
;             int rs = rq - 4; rs = rs < 0 ? 0 : rs; rs = rs > A.R - 8 ? A.R - 8 : rs;
;             if (kr < rs || kr >= rs + 8) {
; #pragma unroll
;                 for (int r = 0; r < 16; ++r) { p0[r] = NEG; p1[r] = NEG; }
;             } else {
;                 const int c = 32 * (qb & 1) + r32; int cs = c - 8; cs = cs < 0 ? 0 : cs; cs = cs > 48 ? 48 : cs;
;                 const float* b = lutB + ((2 * A.h + half) * 15 + (kr - rq + 7)) * 128 + 64 + 4 * hi - c;
; #pragma unroll
;                 for (int r = 0; r < 16; ++r) { const int cc = (r & 3) + 8 * (r >> 2), j = 4 * hi + cc;
;                     p0[r] = ((unsigned)(j - cs) < 16u) ? p0[r] + b[cc] : NEG; p1[r] = ((unsigned)(j + 32 - cs) < 16u) ? p1[r] + b[32 + cc] : NEG; } }
;         }
;         SBAR();
;     };
.LBB0_314:
	s_add_i32 s84, s8, s7
	s_mul_i32 s3, s84, 0x1400
	s_mul_hi_u32 s2, s84, 0x1400
	s_add_u32 s17, s37, s3
	s_addc_u32 s18, s38, s2
	s_lshl_b32 s2, s6, 7
	s_ashr_i32 s3, s2, 31
	s_lshl_b64 s[2:3], s[2:3], 1
	s_add_u32 s24, s17, s2
	s_addc_u32 s25, s18, s3
	s_mul_i32 s31, s7, 0x1400
	s_mul_hi_u32 s30, s7, 0x1400
	s_add_u32 s6, s37, s31
	s_addc_u32 s7, s38, s30
	s_add_u32 s6, s6, s2
	s_addc_u32 s7, s7, s3
	s_and_b32 s18, s1, 3
	v_and_b32_e32 v156, 31, v40
	s_lshl_b32 s28, s18, 5
	v_or_b32_e32 v0, s28, v156
	s_ashr_i32 s17, s0, 8
	v_mul_u32_u24_e32 v144, 0x1400, v0
	v_lshl_add_u64 v[0:1], s[24:25], 0, v[144:145]
	s_lshl_b32 s24, s17, 6
	v_bfe_u32 v157, v40, 5, 1
	s_ashr_i32 s25, s24, 31
	v_lshl_add_u64 v[0:1], s[24:25], 1, v[0:1]
	v_lshlrev_b32_e32 v136, 4, v157
	v_mov_b32_e32 v137, v145
	v_lshl_add_u64 v[0:1], v[0:1], 0, v[136:137]
	global_load_dwordx4 v[108:111], v[0:1], off
	global_load_dwordx4 v[104:107], v[0:1], off offset:32
	global_load_dwordx4 v[100:103], v[0:1], off offset:64
	global_load_dwordx4 v[96:99], v[0:1], off offset:96
	s_setprio 0
	s_add_u32 s24, s6, 0x400
	s_addc_u32 s25, s7, 0
	s_add_u32 s26, s6, 0x800
	s_addc_u32 s27, s7, 0
	v_and_b32_e32 v137, 63, v40
	v_lshlrev_b32_e32 v176, 8, v156
	v_and_b32_e32 v178, 7, v156
	v_lshlrev_b32_e32 v178, 4, v178
	s_lshl_b32 s101, s17, 7
	v_or_b32_e32 v179, s101, v136
	v_xor_b32_e32 v179, v179, v178
	v_add_u32_e32 v176, v176, v179
	v_add_u32_e32 v164, 0x8000, v176
	v_xor_b32_e32 v165, 32, v164
	v_xor_b32_e32 v166, 64, v164
	v_xor_b32_e32 v167, 0x60, v164
	v_and_b32_e32 v176, 3, v137
	v_lshlrev_b32_e32 v176, 3, v176
	v_bfe_u32 v178, v137, 2, 2
	v_lshlrev_b32_e32 v178, 6, v178
	v_bfe_u32 v179, v137, 4, 1
	v_lshlrev_b32_e32 v179, 5, v179
	v_bfe_u32 v180, v137, 5, 1
	v_lshlrev_b32_e32 v180, 8, v180
	v_or3_b32 v176, v176, v178, v179
	v_or_b32_e32 v168, v176, v180
	v_lshrrev_b32_e32 v176, 4, v40
	v_and_b32_e32 v178, 15, v40
	v_and_b32_e32 v179, 7, v176
	v_xor_b32_e32 v178, v178, v179
	v_lshlrev_b32_e32 v178, 4, v178
	v_mul_u32_u24_e32 v176, 0x1400, v176
	v_add_u32_e32 v169, v176, v178
	v_add_u32_e32 v170, 0x28000, v169
	v_bfe_u32 v176, v137, 2, 3
	v_and_b32_e32 v178, 3, v176
	v_lshrrev_b32_e32 v176, 2, v176
	v_lshl_or_b32 v178, v176, 3, v178
	s_bfe_u32 s101, s1, 0x10001
	s_lshl_b32 s101, s101, 2
	s_bfe_u32 s6, s1, 0x10002
	s_lshl_b32 s6, s6, 4
	s_or_b32 s101, s101, s6
	v_or_b32_e32 v178, s101, v178
	v_mul_u32_u24_e32 v178, 0x1400, v178
	s_and_b32 s101, s1, 1
	s_lshl_b32 s101, s101, 7
	v_bfe_u32 v176, v137, 5, 1
	v_lshlrev_b32_e32 v176, 6, v176
	v_and_b32_e32 v179, 3, v137
	v_lshlrev_b32_e32 v179, 4, v179
	v_add3_u32 v178, v178, v176, v179
	v_add_u32_e32 v171, s101, v178
	v_add_u32_e32 v172, 0x28000, v171
	s_lshl_b32 s33, s1, 10
	s_add_u32 s31, s33, 0x8000
	s_add_i32 s101, s8, s28
	s_sub_i32 s29, s101, 0xbf
	s_add_i32 s30, s101, 0x9f
	s_sub_i32 s35, 0x140, s101
	s_lshl_b32 s35, s35, 2
	s_add_i32 s35, s35, s19
	v_lshlrev_b32_e32 v176, 2, v157
	v_sub_u32_e32 v176, v176, v156
	v_lshlrev_b32_e32 v174, 2, v176
	v_mov_b32_e32 v176, s13
	v_sub_f32_e32 v178, s21, v176
	v_sub_f32_e32 v179, s20, v176
	s_xor_b32 s99, s13, 0x80000000
	v_readfirstlane_b32 s98, v178
	v_readfirstlane_b32 s100, v179
	s_sub_i32 s20, s22, 1
	s_mov_b32 s34, 0
	s_mov_b32 s23, 0
	s_cmp_le_i32 s23, s29
	s_cselect_b32 s9, s98, s99
	v_mov_b32_e32 v68, s9
	v_mov_b32_e32 v69, s9
	v_mov_b32_e32 v70, s9
	v_mov_b32_e32 v71, s9
	v_mov_b32_e32 v72, s9
	v_mov_b32_e32 v73, s9
	v_mov_b32_e32 v74, s9
	v_mov_b32_e32 v75, s9
	v_mov_b32_e32 v76, s9
	v_mov_b32_e32 v77, s9
	v_mov_b32_e32 v78, s9
	v_mov_b32_e32 v79, s9
	v_mov_b32_e32 v80, s9
	v_mov_b32_e32 v81, s9
	v_mov_b32_e32 v82, s9
	v_mov_b32_e32 v83, s9
	v_mov_b32_e32 v0, 0
	v_mov_b32_e32 v1, 0
	v_mov_b32_e32 v2, 0
	v_mov_b32_e32 v3, 0
	v_mov_b32_e32 v4, 0
	v_mov_b32_e32 v5, 0
	v_mov_b32_e32 v6, 0
	v_mov_b32_e32 v7, 0
	v_mov_b32_e32 v8, 0
	v_mov_b32_e32 v9, 0
	v_mov_b32_e32 v10, 0
	v_mov_b32_e32 v11, 0
	v_mov_b32_e32 v12, 0
	v_mov_b32_e32 v13, 0
	v_mov_b32_e32 v14, 0
	v_mov_b32_e32 v15, 0
	v_mov_b32_e32 v16, 0
	v_mov_b32_e32 v17, 0
	v_mov_b32_e32 v18, 0
	v_mov_b32_e32 v19, 0
	v_mov_b32_e32 v20, 0
	v_mov_b32_e32 v21, 0
	v_mov_b32_e32 v22, 0
	v_mov_b32_e32 v23, 0
	v_mov_b32_e32 v24, 0
	v_mov_b32_e32 v25, 0
	v_mov_b32_e32 v26, 0
	v_mov_b32_e32 v27, 0
	v_mov_b32_e32 v28, 0
	v_mov_b32_e32 v29, 0
	v_mov_b32_e32 v30, 0
	v_mov_b32_e32 v31, 0
	v_mov_b32_e32 v32, 0
	v_mov_b32_e32 v33, 0
	v_mov_b32_e32 v34, 0
	v_mov_b32_e32 v35, 0
	v_mov_b32_e32 v36, 0
	v_mov_b32_e32 v37, 0
	v_mov_b32_e32 v38, 0
	v_mov_b32_e32 v39, 0
	v_mov_b32_e32 v40, 0
	v_mov_b32_e32 v41, 0
	v_mov_b32_e32 v42, 0
	v_mov_b32_e32 v43, 0
	v_mov_b32_e32 v44, 0
	v_mov_b32_e32 v45, 0
	v_mov_b32_e32 v46, 0
	v_mov_b32_e32 v47, 0
	v_mov_b32_e32 v48, 0
	v_mov_b32_e32 v49, 0
	v_mov_b32_e32 v50, 0
	v_mov_b32_e32 v51, 0
	v_mov_b32_e32 v52, 0
	v_mov_b32_e32 v53, 0
	v_mov_b32_e32 v54, 0
	v_mov_b32_e32 v55, 0
	v_mov_b32_e32 v56, 0
	v_mov_b32_e32 v57, 0
	v_mov_b32_e32 v58, 0
	v_mov_b32_e32 v59, 0
	v_mov_b32_e32 v60, 0
	v_mov_b32_e32 v61, 0
	v_mov_b32_e32 v62, 0
	v_mov_b32_e32 v63, 0
	v_mov_b32_e32 v64, 0
	v_mov_b32_e32 v65, 0
	v_mov_b32_e32 v66, 0
	v_mov_b32_e32 v67, 0
	s_mov_b32 m0, s31
	s_add_u32 s101, s31, 0x2000
	global_load_lds_dwordx4 v169, s[24:25]
	s_mov_b32 m0, s101
	s_xor_b32 s31, s31, 0x4000
	global_load_lds_dwordx4 v170, s[24:25]
	s_add_u32 s24, s24, 0x50000
	s_addc_u32 s25, s25, 0
	s_mov_b32 m0, s31
	s_add_u32 s101, s31, 0x2000
	global_load_lds_dwordx4 v169, s[24:25]
	s_mov_b32 m0, s101
	s_xor_b32 s31, s31, 0x4000
	global_load_lds_dwordx4 v170, s[24:25]
	s_add_u32 s24, s24, 0x50000
	s_addc_u32 s25, s25, 0
	s_mov_b32 m0, s33
	s_add_u32 s101, s33, 0x2000
	global_load_lds_dwordx4 v171, s[26:27]
	s_mov_b32 m0, s101
	s_xor_b32 s33, s33, 0x4000
	global_load_lds_dwordx4 v172, s[26:27]
	s_add_u32 s26, s26, 0x50000
	s_addc_u32 s27, s27, 0
	s_waitcnt vmcnt(0)
	s_barrier
; #define SBAR() __builtin_amdgcn_sched_barrier(0)
; #define KFRAG(d0, row) (*reinterpret_cast<const bf16x8*>(Ks + KSWZ((row), (half * 64 + (d0) * 16 + hi * 8) * 2)))
; __device__ __forceinline__ void expHalf(f32x16& p0) {
; #pragma unroll
;     for (int r = 0; r < 16; ++r) p0[r] = __builtin_amdgcn_exp2f(p0[r]);
; }
; __device__ __forceinline__ void finishSM(f32x16& p0, f32x16& p1, float& l_reg, bf16x8& pa0, bf16x8& pa1, bf16x8& pa2, bf16x8& pa3) {
;     float ps = 0;
; #pragma unroll
;     for (int r = 0; r < 16; ++r) ps += p0[r];
; #pragma unroll
;     for (int r = 0; r < 16; ++r) ps += p1[r];
;     l_reg += ps;
;     ...
;     PK4(p0, 0, pa0); PK4(p0, 8, pa1); PK4(p1, 0, pa2); PK4(p1, 8, pa3);
;     ...
; }
; __device__ __forceinline__ void qkt(f32x16& p0, f32x16& p1, const char* Ks, const bf16x8* qr, float c0, int r32, int hi, int half) {
;     ...
;     bf16x8 a0 = KFRAG(0, r32), a1 = KFRAG(0, 32 + r32), b0 = KFRAG(1, r32), b1 = KFRAG(1, 32 + r32);
;     SBAR();
; #pragma unroll
;     for (int r = 0; r < 16; ++r) { p0[r] = c0; p1[r] = c0; }
;     SBAR();
;     p0 = __builtin_amdgcn_mfma_f32_32x32x16_bf16(a0, qr[0], p0, 0, 0, 0); p1 = __builtin_amdgcn_mfma_f32_32x32x16_bf16(a1, qr[0], p1, 0, 0, 0);
;     a0 = KFRAG(2, r32); a1 = KFRAG(2, 32 + r32);
;     SBAR();
;     p0 = __builtin_amdgcn_mfma_f32_32x32x16_bf16(b0, qr[1], p0, 0, 0, 0); p1 = __builtin_amdgcn_mfma_f32_32x32x16_bf16(b1, qr[1], p1, 0, 0, 0);
;     b0 = KFRAG(3, r32); b1 = KFRAG(3, 32 + r32);
;     SBAR();
;     p0 = __builtin_amdgcn_mfma_f32_32x32x16_bf16(a0, qr[2], p0, 0, 0, 0); p1 = __builtin_amdgcn_mfma_f32_32x32x16_bf16(a1, qr[2], p1, 0, 0, 0);
;     p0 = __builtin_amdgcn_mfma_f32_32x32x16_bf16(b0, qr[3], p0, 0, 0, 0); p1 = __builtin_amdgcn_mfma_f32_32x32x16_bf16(b1, qr[3], p1, 0, 0, 0);
; template <int MODE>
; __device__ __forceinline__ void attn_unit(const UnitArgs& A, char* lds, const int wave_) {
;     ...
;     auto post = [&](f32x16& p0, f32x16& p1, int t) {
;         SBAR();
;         if (MODE == 0) {
;             if (zone_of(t) == 1) { const int k0 = 64 * t, qw0 = A.q0 + 32 * qb;
;                 const float* b = lutA + A.h * LUTA_STRIDE + (k0 - qw0 - r32 + 4 * hi + 320);
; #pragma unroll
;                 for (int r = 0; r < 16; ++r) { const int c = (r & 3) + 8 * (r >> 2); p0[r] += b[c]; p1[r] += b[32 + c]; } }
	s_cmp_lg_u32 s17, 0
	s_cbranch_scc1 .Lat_g1
	ds_read_b128 v[224:227], v164
	ds_read_b128 v[228:231], v164 offset:8192
	ds_read_b128 v[232:235], v165
	ds_read_b128 v[236:239], v165 offset:8192
	ds_read_b128 v[240:243], v166
	ds_read_b128 v[244:247], v166 offset:8192
	ds_read_b128 v[248:251], v167
	ds_read_b128 v[188:191], v167 offset:8192
	v_xor_b32_e32 v164, 0x4000, v164
	v_xor_b32_e32 v165, 0x4000, v165
	v_xor_b32_e32 v166, 0x4000, v166
	v_xor_b32_e32 v167, 0x4000, v167
	s_waitcnt lgkmcnt(7)
	v_mfma_f32_32x32x16_bf16 v[112:127], v[224:227], v[108:111], v[68:83]
	s_waitcnt lgkmcnt(6)
	v_mfma_f32_32x32x16_bf16 v[192:207], v[228:231], v[108:111], v[68:83]
	s_waitcnt lgkmcnt(5)
	v_mfma_f32_32x32x16_bf16 v[112:127], v[232:235], v[104:107], v[112:127]
	s_waitcnt lgkmcnt(4)
	v_mfma_f32_32x32x16_bf16 v[192:207], v[236:239], v[104:107], v[192:207]
	s_waitcnt lgkmcnt(3)
	v_mfma_f32_32x32x16_bf16 v[112:127], v[240:243], v[100:103], v[112:127]
	s_waitcnt lgkmcnt(2)
	v_mfma_f32_32x32x16_bf16 v[192:207], v[244:247], v[100:103], v[192:207]
	s_waitcnt lgkmcnt(1)
	v_mfma_f32_32x32x16_bf16 v[112:127], v[248:251], v[96:99], v[112:127]
	s_waitcnt lgkmcnt(0)
	v_mfma_f32_32x32x16_bf16 v[192:207], v[188:191], v[96:99], v[192:207]
	s_nop 7
	s_nop 3
	s_barrier
.Lat_g0_loop:
	s_cmp_gt_i32 s23, s29
	s_cselect_b32 s101, 1, 0
	s_cmp_lt_i32 s23, s30
	s_cselect_b32 s6, 1, 0
	s_and_b32 s101, s101, s6
	s_cbranch_scc0 .Lat_far_g0l
	v_add_u32_e32 v181, s35, v174
	ds_read2_b32 v[224:225], v181 offset0:0 offset1:1
	ds_read2_b32 v[226:227], v181 offset0:2 offset1:3
	ds_read2_b32 v[228:229], v181 offset0:8 offset1:9
	ds_read2_b32 v[230:231], v181 offset0:10 offset1:11
	ds_read2_b32 v[232:233], v181 offset0:16 offset1:17
	ds_read2_b32 v[234:235], v181 offset0:18 offset1:19
	ds_read2_b32 v[236:237], v181 offset0:24 offset1:25
	ds_read2_b32 v[238:239], v181 offset0:26 offset1:27
	s_waitcnt lgkmcnt(4)
	ds_read2_b32 v[240:241], v181 offset0:32 offset1:33
	ds_read2_b32 v[242:243], v181 offset0:34 offset1:35
	ds_read2_b32 v[244:245], v181 offset0:40 offset1:41
	ds_read2_b32 v[246:247], v181 offset0:42 offset1:43
	ds_read2_b32 v[248:249], v181 offset0:48 offset1:49
	ds_read2_b32 v[250:251], v181 offset0:50 offset1:51
	ds_read2_b32 v[188:189], v181 offset0:56 offset1:57
	ds_read2_b32 v[190:191], v181 offset0:58 offset1:59
	s_waitcnt lgkmcnt(8)
	v_add_f32_e32 v112, v112, v224
	v_add_f32_e32 v113, v113, v225
	v_add_f32_e32 v114, v114, v226
	v_add_f32_e32 v115, v115, v227
	v_add_f32_e32 v116, v116, v228
	v_add_f32_e32 v117, v117, v229
	v_add_f32_e32 v118, v118, v230
	v_add_f32_e32 v119, v119, v231
	v_add_f32_e32 v120, v120, v232
	v_add_f32_e32 v121, v121, v233
	v_add_f32_e32 v122, v122, v234
	v_add_f32_e32 v123, v123, v235
	v_add_f32_e32 v124, v124, v236
	v_add_f32_e32 v125, v125, v237
	v_add_f32_e32 v126, v126, v238
	v_add_f32_e32 v127, v127, v239
	s_waitcnt lgkmcnt(0)
	v_add_f32_e32 v192, v192, v240
	v_add_f32_e32 v193, v193, v241
	v_add_f32_e32 v194, v194, v242
	v_add_f32_e32 v195, v195, v243
	v_add_f32_e32 v196, v196, v244
	v_add_f32_e32 v197, v197, v245
	v_add_f32_e32 v198, v198, v246
	v_add_f32_e32 v199, v199, v247
	v_add_f32_e32 v200, v200, v248
	v_add_f32_e32 v201, v201, v249
	v_add_f32_e32 v202, v202, v250
	v_add_f32_e32 v203, v203, v251
	v_add_f32_e32 v204, v204, v188
	v_add_f32_e32 v205, v205, v189
	v_add_f32_e32 v206, v206, v190
	v_add_f32_e32 v207, v207, v191
.Lat_far_g0l:
	v_exp_f32_e32 v112, v112
	v_exp_f32_e32 v113, v113
	v_exp_f32_e32 v114, v114
	v_exp_f32_e32 v115, v115
	v_exp_f32_e32 v116, v116
	v_exp_f32_e32 v117, v117
	v_exp_f32_e32 v118, v118
	v_exp_f32_e32 v119, v119
	v_exp_f32_e32 v120, v120
	v_exp_f32_e32 v121, v121
	v_exp_f32_e32 v122, v122
	v_exp_f32_e32 v123, v123
	v_exp_f32_e32 v124, v124
	v_exp_f32_e32 v125, v125
	v_exp_f32_e32 v126, v126
	v_exp_f32_e32 v127, v127
	v_exp_f32_e32 v192, v192
	v_add_f32_e32 v64, v64, v112
	v_exp_f32_e32 v193, v193
	v_add_f32_e32 v65, v65, v113
	v_exp_f32_e32 v194, v194
	v_add_f32_e32 v66, v66, v114
	v_exp_f32_e32 v195, v195
	v_add_f32_e32 v67, v67, v115
	v_exp_f32_e32 v196, v196
	v_add_f32_e32 v64, v64, v116
	v_exp_f32_e32 v197, v197
	v_add_f32_e32 v65, v65, v117
	v_exp_f32_e32 v198, v198
	v_add_f32_e32 v66, v66, v118
	v_exp_f32_e32 v199, v199
	v_add_f32_e32 v67, v67, v119
	v_exp_f32_e32 v200, v200
	v_add_f32_e32 v64, v64, v120
	v_exp_f32_e32 v201, v201
	v_add_f32_e32 v65, v65, v121
	v_exp_f32_e32 v202, v202
	v_add_f32_e32 v66, v66, v122
	v_exp_f32_e32 v203, v203
	v_add_f32_e32 v67, v67, v123
	v_exp_f32_e32 v204, v204
	v_add_f32_e32 v64, v64, v124
	v_exp_f32_e32 v205, v205
	v_add_f32_e32 v65, v65, v125
	v_exp_f32_e32 v206, v206
	v_add_f32_e32 v66, v66, v126
	v_exp_f32_e32 v207, v207
	v_add_f32_e32 v67, v67, v127
	v_cvt_pk_bf16_f32 v208, v112, v113
	v_cvt_pk_bf16_f32 v209, v114, v115
	v_cvt_pk_bf16_f32 v210, v116, v117
	v_cvt_pk_bf16_f32 v211, v118, v119
	v_cvt_pk_bf16_f32 v212, v120, v121
	v_cvt_pk_bf16_f32 v213, v122, v123
	v_cvt_pk_bf16_f32 v214, v124, v125
	v_cvt_pk_bf16_f32 v215, v126, v127
	v_add_f32_e32 v64, v64, v192
	v_add_f32_e32 v65, v65, v193
	v_add_f32_e32 v66, v66, v194
	v_add_f32_e32 v67, v67, v195
	v_add_f32_e32 v64, v64, v196
	v_add_f32_e32 v65, v65, v197
	v_add_f32_e32 v66, v66, v198
	v_add_f32_e32 v67, v67, v199
	v_permlane32_swap_b32_e32 v208, v210
	v_permlane32_swap_b32_e32 v209, v211
	v_permlane32_swap_b32_e32 v212, v214
	v_permlane32_swap_b32_e32 v213, v215
	v_add_f32_e32 v64, v64, v200
	v_add_f32_e32 v65, v65, v201
	v_add_f32_e32 v66, v66, v202
	v_add_f32_e32 v67, v67, v203
	v_add_f32_e32 v64, v64, v204
	v_add_f32_e32 v65, v65, v205
	v_add_f32_e32 v66, v66, v206
	v_add_f32_e32 v67, v67, v207
	v_cvt_pk_bf16_f32 v216, v192, v193
	v_cvt_pk_bf16_f32 v217, v194, v195
	v_cvt_pk_bf16_f32 v218, v196, v197
	v_cvt_pk_bf16_f32 v219, v198, v199
	v_cvt_pk_bf16_f32 v220, v200, v201
	v_cvt_pk_bf16_f32 v221, v202, v203
	v_cvt_pk_bf16_f32 v222, v204, v205
	v_cvt_pk_bf16_f32 v223, v206, v207
	s_add_i32 s101, s23, 64
	s_cmp_ge_i32 s101, s30
	s_cselect_b32 s6, s100, s99
	s_cmp_le_i32 s101, s29
	s_cselect_b32 s6, s98, s6
	s_nop 0
	v_permlane32_swap_b32_e32 v216, v218
	v_permlane32_swap_b32_e32 v217, v219
	v_permlane32_swap_b32_e32 v220, v222
	v_permlane32_swap_b32_e32 v221, v223
	s_cmp_lg_u32 s6, s9
	s_cbranch_scc0 .Lat_c0same_g0l
	s_mov_b32 s9, s6
	v_mov_b32_e32 v68, s9
	v_mov_b32_e32 v69, s9
	v_mov_b32_e32 v70, s9
	v_mov_b32_e32 v71, s9
	v_mov_b32_e32 v72, s9
	v_mov_b32_e32 v73, s9
	v_mov_b32_e32 v74, s9
	v_mov_b32_e32 v75, s9
	v_mov_b32_e32 v76, s9
	v_mov_b32_e32 v77, s9
	v_mov_b32_e32 v78, s9
	v_mov_b32_e32 v79, s9
	v_mov_b32_e32 v80, s9
	v_mov_b32_e32 v81, s9
	v_mov_b32_e32 v82, s9
	v_mov_b32_e32 v83, s9
; #define SBAR() __builtin_amdgcn_sched_barrier(0)
; __device__ __forceinline__ void qkt(f32x16& p0, f32x16& p1, const char* Ks, const bf16x8* qr, float c0, int r32, int hi, int half) {
;     ...
;     bf16x8 a0 = KFRAG(0, r32), a1 = KFRAG(0, 32 + r32), b0 = KFRAG(1, r32), b1 = KFRAG(1, 32 + r32);
;     SBAR();
; #pragma unroll
;     for (int r = 0; r < 16; ++r) { p0[r] = c0; p1[r] = c0; }
;     SBAR();
;     p0 = __builtin_amdgcn_mfma_f32_32x32x16_bf16(a0, qr[0], p0, 0, 0, 0); p1 = __builtin_amdgcn_mfma_f32_32x32x16_bf16(a1, qr[0], p1, 0, 0, 0);
;     a0 = KFRAG(2, r32); a1 = KFRAG(2, 32 + r32);
;     SBAR();
;     p0 = __builtin_amdgcn_mfma_f32_32x32x16_bf16(b0, qr[1], p0, 0, 0, 0); p1 = __builtin_amdgcn_mfma_f32_32x32x16_bf16(b1, qr[1], p1, 0, 0, 0);
;     b0 = KFRAG(3, r32); b1 = KFRAG(3, 32 + r32);
;     SBAR();
;     p0 = __builtin_amdgcn_mfma_f32_32x32x16_bf16(a0, qr[2], p0, 0, 0, 0); p1 = __builtin_amdgcn_mfma_f32_32x32x16_bf16(a1, qr[2], p1, 0, 0, 0);
;     p0 = __builtin_amdgcn_mfma_f32_32x32x16_bf16(b0, qr[3], p0, 0, 0, 0); p1 = __builtin_amdgcn_mfma_f32_32x32x16_bf16(b1, qr[3], p1, 0, 0, 0);
;     ...
; }
; __device__ __forceinline__ int v_st(int k, int c) { const int kk = (k & ~0xC) | ((k & 4) << 1) | ((k & 8) >> 1); return ((kk >> 3) * 4 + (c >> 5)) * 512 + ((kk & 7) * 32 + (c & 31)) * 2; }
; __device__ __forceinline__ int v_rd_base(int lane) { return ((lane & 3) << 3) | (((lane >> 2) & 3) << 6) | (((lane >> 4) & 1) << 5) | (((lane >> 5) & 1) << 8); }
; template <int OFF> __device__ __forceinline__ s16x4 tr_read(int vb) { s16x4 r; asm volatile("ds_read_b64_tr_b16 %0, %1 offset:%2" : "=&v"(r) : "v"(vb), "i"(OFF) : "memory"); return r; }
; template <int NB> __device__ __forceinline__ void pv_blocks(f32x16* o, int vb, bf16x8 pa0, bf16x8 pa1, bf16x8 pa2, bf16x8 pa3, f32x16& pe0, f32x16& pe1) {
;     s16x4 x[8], y[8];
;     ...
;     PVLOAD(0, x); PVWAIT();
;     if (NB == 4) {
;         PVLOAD(1, y); SBAR(); PVMMA(o[0], x); PVEXP(pe0, 0, 8); SBAR(); PVWAIT();
;         PVLOAD(2, x); SBAR(); PVMMA(o[1], y); PVEXP(pe0, 8, 8); SBAR(); PVWAIT();
;         PVLOAD(3, y); SBAR(); PVMMA(o[2], x); PVEXP(pe1, 0, 8); SBAR(); PVWAIT();
;         PVMMA(o[3], y); PVEXP(pe1, 8, 8);
;     } else {
;         PVLOAD(1, y); SBAR(); PVMMA(o[0], x); PVEXP(pe0, 0, 16); SBAR(); PVWAIT();
;         PVMMA(o[1], y); PVEXP(pe1, 0, 16);
;     }
;     ...
; }
.Lat_c0same_g0l:
	s_waitcnt vmcnt(0)
	s_barrier
	s_mov_b32 m0, s31
	s_add_u32 s101, s31, 0x2000
	global_load_lds_dwordx4 v169, s[24:25]
	s_mov_b32 m0, s101
	s_xor_b32 s31, s31, 0x4000
	global_load_lds_dwordx4 v170, s[24:25]
	s_mov_b32 m0, s33
	s_add_u32 s101, s33, 0x2000
	global_load_lds_dwordx4 v171, s[26:27]
	s_mov_b32 m0, s101
	s_xor_b32 s33, s33, 0x4000
	global_load_lds_dwordx4 v172, s[26:27]
	s_add_u32 s24, s24, 0x50000
	s_addc_u32 s25, s25, 0
	s_add_u32 s26, s26, 0x50000
	s_addc_u32 s27, s27, 0
	ds_read_b128 v[224:227], v164
	ds_read_b128 v[228:231], v164 offset:8192
	ds_read_b128 v[232:235], v165
	ds_read_b128 v[236:239], v165 offset:8192
	ds_read_b128 v[240:243], v166
	ds_read_b128 v[244:247], v166 offset:8192
	ds_read_b128 v[248:251], v167
	ds_read_b128 v[188:191], v167 offset:8192
	v_xor_b32_e32 v164, 0x4000, v164
	v_xor_b32_e32 v165, 0x4000, v165
	v_xor_b32_e32 v166, 0x4000, v166
	v_xor_b32_e32 v167, 0x4000, v167
	s_waitcnt lgkmcnt(7)
	v_mfma_f32_32x32x16_bf16 v[112:127], v[224:227], v[108:111], v[68:83]
	s_waitcnt lgkmcnt(6)
	v_mfma_f32_32x32x16_bf16 v[192:207], v[228:231], v[108:111], v[68:83]
	ds_read_b64_tr_b16 v[84:85], v168 offset:0
	ds_read_b64_tr_b16 v[86:87], v168 offset:2048
	s_waitcnt lgkmcnt(7)
	v_mfma_f32_32x32x16_bf16 v[112:127], v[232:235], v[104:107], v[112:127]
	ds_read_b64_tr_b16 v[88:89], v168 offset:4096
	ds_read_b64_tr_b16 v[90:91], v168 offset:6144
	s_waitcnt lgkmcnt(8)
	v_mfma_f32_32x32x16_bf16 v[192:207], v[236:239], v[104:107], v[192:207]
	ds_read_b64_tr_b16 v[92:93], v168 offset:8192
	ds_read_b64_tr_b16 v[94:95], v168 offset:10240
	s_waitcnt lgkmcnt(9)
	v_mfma_f32_32x32x16_bf16 v[112:127], v[240:243], v[100:103], v[112:127]
	ds_read_b64_tr_b16 v[128:129], v168 offset:12288
	ds_read_b64_tr_b16 v[130:131], v168 offset:14336
	s_waitcnt lgkmcnt(10)
	v_mfma_f32_32x32x16_bf16 v[192:207], v[244:247], v[100:103], v[192:207]
	ds_read_b64_tr_b16 v[132:133], v168 offset:512
	ds_read_b64_tr_b16 v[134:135], v168 offset:2560
	s_waitcnt lgkmcnt(11)
	v_mfma_f32_32x32x16_bf16 v[112:127], v[248:251], v[96:99], v[112:127]
	ds_read_b64_tr_b16 v[140:141], v168 offset:4608
	ds_read_b64_tr_b16 v[142:143], v168 offset:6656
	s_waitcnt lgkmcnt(12)
	v_mfma_f32_32x32x16_bf16 v[192:207], v[188:191], v[96:99], v[192:207]
	ds_read_b64_tr_b16 v[152:153], v168 offset:8704
	ds_read_b64_tr_b16 v[154:155], v168 offset:10752
	s_waitcnt lgkmcnt(12)
	v_mfma_f32_32x32x16_bf16 v[0:15], v[208:211], v[84:87], v[0:15]
	ds_read_b64_tr_b16 v[160:161], v168 offset:12800
	ds_read_b64_tr_b16 v[162:163], v168 offset:14848
	s_waitcnt lgkmcnt(12)
	v_mfma_f32_32x32x16_bf16 v[0:15], v[212:215], v[88:91], v[0:15]
	ds_read_b64_tr_b16 v[84:85], v168 offset:1024
	ds_read_b64_tr_b16 v[86:87], v168 offset:3072
	s_waitcnt lgkmcnt(12)
	v_mfma_f32_32x32x16_bf16 v[0:15], v[216:219], v[92:95], v[0:15]
	ds_read_b64_tr_b16 v[88:89], v168 offset:5120
	ds_read_b64_tr_b16 v[90:91], v168 offset:7168
	s_waitcnt lgkmcnt(12)
	v_mfma_f32_32x32x16_bf16 v[0:15], v[220:223], v[128:131], v[0:15]
	ds_read_b64_tr_b16 v[92:93], v168 offset:9216
	ds_read_b64_tr_b16 v[94:95], v168 offset:11264
	s_waitcnt lgkmcnt(12)
	v_mfma_f32_32x32x16_bf16 v[16:31], v[208:211], v[132:135], v[16:31]
	ds_read_b64_tr_b16 v[128:129], v168 offset:13312
	ds_read_b64_tr_b16 v[130:131], v168 offset:15360
	s_waitcnt lgkmcnt(12)
	v_mfma_f32_32x32x16_bf16 v[16:31], v[212:215], v[140:143], v[16:31]
	ds_read_b64_tr_b16 v[132:133], v168 offset:1536
	ds_read_b64_tr_b16 v[134:135], v168 offset:3584
	s_waitcnt lgkmcnt(12)
	v_mfma_f32_32x32x16_bf16 v[16:31], v[216:219], v[152:155], v[16:31]
	ds_read_b64_tr_b16 v[140:141], v168 offset:5632
	ds_read_b64_tr_b16 v[142:143], v168 offset:7680
	s_waitcnt lgkmcnt(12)
	v_mfma_f32_32x32x16_bf16 v[16:31], v[220:223], v[160:163], v[16:31]
	ds_read_b64_tr_b16 v[152:153], v168 offset:9728
	ds_read_b64_tr_b16 v[154:155], v168 offset:11776
	s_waitcnt lgkmcnt(12)
	v_mfma_f32_32x32x16_bf16 v[32:47], v[208:211], v[84:87], v[32:47]
	ds_read_b64_tr_b16 v[160:161], v168 offset:13824
	ds_read_b64_tr_b16 v[162:163], v168 offset:15872
	v_xor_b32_e32 v168, 0x4000, v168
	s_waitcnt lgkmcnt(12)
	v_mfma_f32_32x32x16_bf16 v[32:47], v[212:215], v[88:91], v[32:47]
	s_waitcnt lgkmcnt(10)
	v_mfma_f32_32x32x16_bf16 v[32:47], v[216:219], v[92:95], v[32:47]
	s_waitcnt lgkmcnt(8)
	v_mfma_f32_32x32x16_bf16 v[32:47], v[220:223], v[128:131], v[32:47]
	s_waitcnt lgkmcnt(6)
	v_mfma_f32_32x32x16_bf16 v[48:63], v[208:211], v[132:135], v[48:63]
	s_waitcnt lgkmcnt(4)
	v_mfma_f32_32x32x16_bf16 v[48:63], v[212:215], v[140:143], v[48:63]
	s_waitcnt lgkmcnt(2)
	v_mfma_f32_32x32x16_bf16 v[48:63], v[216:219], v[152:155], v[48:63]
	s_waitcnt lgkmcnt(0)
	v_mfma_f32_32x32x16_bf16 v[48:63], v[220:223], v[160:163], v[48:63]
	s_add_i32 s34, s34, 1
	s_add_i32 s23, s23, 64
	s_addk_i32 s35, 0x100
	s_barrier
	s_cmp_lt_u32 s34, s20
	s_cbranch_scc1 .Lat_g0_loop
	s_cmp_gt_i32 s23, s29
	s_cselect_b32 s101, 1, 0
	s_cmp_lt_i32 s23, s30
	s_cselect_b32 s6, 1, 0
	s_and_b32 s101, s101, s6
	s_cbranch_scc0 .Lat_far_g0p
	v_add_u32_e32 v181, s35, v174
	ds_read2_b32 v[224:225], v181 offset0:0 offset1:1
	ds_read2_b32 v[226:227], v181 offset0:2 offset1:3
	ds_read2_b32 v[228:229], v181 offset0:8 offset1:9
	ds_read2_b32 v[230:231], v181 offset0:10 offset1:11
	ds_read2_b32 v[232:233], v181 offset0:16 offset1:17
	ds_read2_b32 v[234:235], v181 offset0:18 offset1:19
	ds_read2_b32 v[236:237], v181 offset0:24 offset1:25
	ds_read2_b32 v[238:239], v181 offset0:26 offset1:27
	s_waitcnt lgkmcnt(4)
	ds_read2_b32 v[240:241], v181 offset0:32 offset1:33
	ds_read2_b32 v[242:243], v181 offset0:34 offset1:35
	ds_read2_b32 v[244:245], v181 offset0:40 offset1:41
	ds_read2_b32 v[246:247], v181 offset0:42 offset1:43
	ds_read2_b32 v[248:249], v181 offset0:48 offset1:49
	ds_read2_b32 v[250:251], v181 offset0:50 offset1:51
	ds_read2_b32 v[188:189], v181 offset0:56 offset1:57
	ds_read2_b32 v[190:191], v181 offset0:58 offset1:59
	s_waitcnt lgkmcnt(8)
	v_add_f32_e32 v112, v112, v224
	v_add_f32_e32 v113, v113, v225
	v_add_f32_e32 v114, v114, v226
	v_add_f32_e32 v115, v115, v227
	v_add_f32_e32 v116, v116, v228
	v_add_f32_e32 v117, v117, v229
	v_add_f32_e32 v118, v118, v230
	v_add_f32_e32 v119, v119, v231
	v_add_f32_e32 v120, v120, v232
	v_add_f32_e32 v121, v121, v233
	v_add_f32_e32 v122, v122, v234
	v_add_f32_e32 v123, v123, v235
	v_add_f32_e32 v124, v124, v236
	v_add_f32_e32 v125, v125, v237
	v_add_f32_e32 v126, v126, v238
	v_add_f32_e32 v127, v127, v239
	s_waitcnt lgkmcnt(0)
	v_add_f32_e32 v192, v192, v240
	v_add_f32_e32 v193, v193, v241
	v_add_f32_e32 v194, v194, v242
	v_add_f32_e32 v195, v195, v243
	v_add_f32_e32 v196, v196, v244
	v_add_f32_e32 v197, v197, v245
	v_add_f32_e32 v198, v198, v246
	v_add_f32_e32 v199, v199, v247
	v_add_f32_e32 v200, v200, v248
	v_add_f32_e32 v201, v201, v249
	v_add_f32_e32 v202, v202, v250
	v_add_f32_e32 v203, v203, v251
	v_add_f32_e32 v204, v204, v188
	v_add_f32_e32 v205, v205, v189
	v_add_f32_e32 v206, v206, v190
	v_add_f32_e32 v207, v207, v191
; #define SBAR() __builtin_amdgcn_sched_barrier(0)
; #define PVLOAD(D0, X) do { X[0] = tr_read<v_rd_off(D0, 0, 0)>(vb); X[1] = tr_read<v_rd_off(D0, 0, 1)>(vb); X[2] = tr_read<v_rd_off(D0, 1, 0)>(vb); X[3] = tr_read<v_rd_off(D0, 1, 1)>(vb); \
;     X[4] = tr_read<v_rd_off(D0, 2, 0)>(vb); X[5] = tr_read<v_rd_off(D0, 2, 1)>(vb); X[6] = tr_read<v_rd_off(D0, 3, 0)>(vb); X[7] = tr_read<v_rd_off(D0, 3, 1)>(vb); } while (0)
; #define PVMMA(OD, X) do { OD = __builtin_amdgcn_mfma_f32_32x32x16_bf16(pa0, PVPK(X[0], X[1]), OD, 0, 0, 0); OD = __builtin_amdgcn_mfma_f32_32x32x16_bf16(pa1, PVPK(X[2], X[3]), OD, 0, 0, 0); \
;     OD = __builtin_amdgcn_mfma_f32_32x32x16_bf16(pa2, PVPK(X[4], X[5]), OD, 0, 0, 0); OD = __builtin_amdgcn_mfma_f32_32x32x16_bf16(pa3, PVPK(X[6], X[7]), OD, 0, 0, 0); } while (0)
; #define PVWAIT() do { asm volatile("s_waitcnt lgkmcnt(0)" ::: "memory"); SBAR(); } while (0)
; #define PVEXP(P, B, N) do { _Pragma("unroll") for (int r = (B); r < (B) + (N); ++r) P[r] = __builtin_amdgcn_exp2f(P[r]); } while (0)
; __device__ __forceinline__ void expHalf(f32x16& p0) {
; #pragma unroll
;     for (int r = 0; r < 16; ++r) p0[r] = __builtin_amdgcn_exp2f(p0[r]);
; }
; __device__ __forceinline__ void finishSM(f32x16& p0, f32x16& p1, float& l_reg, bf16x8& pa0, bf16x8& pa1, bf16x8& pa2, bf16x8& pa3) {
;     float ps = 0;
; #pragma unroll
;     for (int r = 0; r < 16; ++r) ps += p0[r];
; #pragma unroll
;     for (int r = 0; r < 16; ++r) ps += p1[r];
;     l_reg += ps;
;     ...
;     PK4(p0, 0, pa0); PK4(p0, 8, pa1); PK4(p1, 0, pa2); PK4(p1, 8, pa3);
;     ...
; }
; template <int NB> __device__ __forceinline__ void pv_blocks(f32x16* o, int vb, bf16x8 pa0, bf16x8 pa1, bf16x8 pa2, bf16x8 pa3, f32x16& pe0, f32x16& pe1) {
;     s16x4 x[8], y[8];
;     ...
;     PVLOAD(0, x); PVWAIT();
;     if (NB == 4) {
;         PVLOAD(1, y); SBAR(); PVMMA(o[0], x); PVEXP(pe0, 0, 8); SBAR(); PVWAIT();
;         PVLOAD(2, x); SBAR(); PVMMA(o[1], y); PVEXP(pe0, 8, 8); SBAR(); PVWAIT();
;         PVLOAD(3, y); SBAR(); PVMMA(o[2], x); PVEXP(pe1, 0, 8); SBAR(); PVWAIT();
;         PVMMA(o[3], y); PVEXP(pe1, 8, 8);
;     } else {
;         PVLOAD(1, y); SBAR(); PVMMA(o[0], x); PVEXP(pe0, 0, 16); SBAR(); PVWAIT();
;         PVMMA(o[1], y); PVEXP(pe1, 0, 16);
;     }
;     ...
; }
.Lat_far_g0p:
	v_exp_f32_e32 v112, v112
	v_exp_f32_e32 v113, v113
	v_exp_f32_e32 v114, v114
	v_exp_f32_e32 v115, v115
	v_exp_f32_e32 v116, v116
	v_exp_f32_e32 v117, v117
	v_exp_f32_e32 v118, v118
	v_exp_f32_e32 v119, v119
	v_exp_f32_e32 v120, v120
	v_exp_f32_e32 v121, v121
	v_exp_f32_e32 v122, v122
	v_exp_f32_e32 v123, v123
	v_exp_f32_e32 v124, v124
	v_exp_f32_e32 v125, v125
	v_exp_f32_e32 v126, v126
	v_exp_f32_e32 v127, v127
	v_exp_f32_e32 v192, v192
	v_add_f32_e32 v64, v64, v112
	v_exp_f32_e32 v193, v193
	v_add_f32_e32 v65, v65, v113
	v_exp_f32_e32 v194, v194
	v_add_f32_e32 v66, v66, v114
	v_exp_f32_e32 v195, v195
	v_add_f32_e32 v67, v67, v115
	v_exp_f32_e32 v196, v196
	v_add_f32_e32 v64, v64, v116
	v_exp_f32_e32 v197, v197
	v_add_f32_e32 v65, v65, v117
	v_exp_f32_e32 v198, v198
	v_add_f32_e32 v66, v66, v118
	v_exp_f32_e32 v199, v199
	v_add_f32_e32 v67, v67, v119
	v_exp_f32_e32 v200, v200
	v_add_f32_e32 v64, v64, v120
	v_exp_f32_e32 v201, v201
	v_add_f32_e32 v65, v65, v121
	v_exp_f32_e32 v202, v202
	v_add_f32_e32 v66, v66, v122
	v_exp_f32_e32 v203, v203
	v_add_f32_e32 v67, v67, v123
	v_exp_f32_e32 v204, v204
	v_add_f32_e32 v64, v64, v124
	v_exp_f32_e32 v205, v205
	v_add_f32_e32 v65, v65, v125
	v_exp_f32_e32 v206, v206
	v_add_f32_e32 v66, v66, v126
	v_exp_f32_e32 v207, v207
	v_add_f32_e32 v67, v67, v127
	v_cvt_pk_bf16_f32 v208, v112, v113
	v_cvt_pk_bf16_f32 v209, v114, v115
	v_cvt_pk_bf16_f32 v210, v116, v117
	v_cvt_pk_bf16_f32 v211, v118, v119
	v_cvt_pk_bf16_f32 v212, v120, v121
	v_cvt_pk_bf16_f32 v213, v122, v123
	v_cvt_pk_bf16_f32 v214, v124, v125
	v_cvt_pk_bf16_f32 v215, v126, v127
	v_add_f32_e32 v64, v64, v192
	v_add_f32_e32 v65, v65, v193
	v_add_f32_e32 v66, v66, v194
	v_add_f32_e32 v67, v67, v195
	v_add_f32_e32 v64, v64, v196
	v_add_f32_e32 v65, v65, v197
	v_add_f32_e32 v66, v66, v198
	v_add_f32_e32 v67, v67, v199
	v_permlane32_swap_b32_e32 v208, v210
	v_permlane32_swap_b32_e32 v209, v211
	v_permlane32_swap_b32_e32 v212, v214
	v_permlane32_swap_b32_e32 v213, v215
	v_add_f32_e32 v64, v64, v200
	v_add_f32_e32 v65, v65, v201
	v_add_f32_e32 v66, v66, v202
	v_add_f32_e32 v67, v67, v203
	v_add_f32_e32 v64, v64, v204
	v_add_f32_e32 v65, v65, v205
	v_add_f32_e32 v66, v66, v206
	v_add_f32_e32 v67, v67, v207
	v_cvt_pk_bf16_f32 v216, v192, v193
	v_cvt_pk_bf16_f32 v217, v194, v195
	v_cvt_pk_bf16_f32 v218, v196, v197
	v_cvt_pk_bf16_f32 v219, v198, v199
	v_cvt_pk_bf16_f32 v220, v200, v201
	v_cvt_pk_bf16_f32 v221, v202, v203
	v_cvt_pk_bf16_f32 v222, v204, v205
	v_cvt_pk_bf16_f32 v223, v206, v207
	s_nop 1
	v_permlane32_swap_b32_e32 v216, v218
	v_permlane32_swap_b32_e32 v217, v219
	v_permlane32_swap_b32_e32 v220, v222
	v_permlane32_swap_b32_e32 v221, v223
	s_waitcnt vmcnt(0)
	s_barrier
	ds_read_b64_tr_b16 v[84:85], v168 offset:0
	ds_read_b64_tr_b16 v[86:87], v168 offset:2048
	ds_read_b64_tr_b16 v[88:89], v168 offset:4096
	ds_read_b64_tr_b16 v[90:91], v168 offset:6144
	ds_read_b64_tr_b16 v[92:93], v168 offset:8192
	ds_read_b64_tr_b16 v[94:95], v168 offset:10240
	ds_read_b64_tr_b16 v[128:129], v168 offset:12288
	ds_read_b64_tr_b16 v[130:131], v168 offset:14336
	ds_read_b64_tr_b16 v[132:133], v168 offset:512
	ds_read_b64_tr_b16 v[134:135], v168 offset:2560
	ds_read_b64_tr_b16 v[140:141], v168 offset:4608
	ds_read_b64_tr_b16 v[142:143], v168 offset:6656
	ds_read_b64_tr_b16 v[152:153], v168 offset:8704
	ds_read_b64_tr_b16 v[154:155], v168 offset:10752
	s_waitcnt lgkmcnt(12)
	v_mfma_f32_32x32x16_bf16 v[0:15], v[208:211], v[84:87], v[0:15]
	ds_read_b64_tr_b16 v[160:161], v168 offset:12800
	ds_read_b64_tr_b16 v[162:163], v168 offset:14848
	s_waitcnt lgkmcnt(12)
	v_mfma_f32_32x32x16_bf16 v[0:15], v[212:215], v[88:91], v[0:15]
	ds_read_b64_tr_b16 v[84:85], v168 offset:1024
	ds_read_b64_tr_b16 v[86:87], v168 offset:3072
	s_waitcnt lgkmcnt(12)
	v_mfma_f32_32x32x16_bf16 v[0:15], v[216:219], v[92:95], v[0:15]
	ds_read_b64_tr_b16 v[88:89], v168 offset:5120
	ds_read_b64_tr_b16 v[90:91], v168 offset:7168
	s_waitcnt lgkmcnt(12)
	v_mfma_f32_32x32x16_bf16 v[0:15], v[220:223], v[128:131], v[0:15]
	ds_read_b64_tr_b16 v[92:93], v168 offset:9216
	ds_read_b64_tr_b16 v[94:95], v168 offset:11264
	s_waitcnt lgkmcnt(12)
	v_mfma_f32_32x32x16_bf16 v[16:31], v[208:211], v[132:135], v[16:31]
	ds_read_b64_tr_b16 v[128:129], v168 offset:13312
	ds_read_b64_tr_b16 v[130:131], v168 offset:15360
	s_waitcnt lgkmcnt(12)
	v_mfma_f32_32x32x16_bf16 v[16:31], v[212:215], v[140:143], v[16:31]
	ds_read_b64_tr_b16 v[132:133], v168 offset:1536
	ds_read_b64_tr_b16 v[134:135], v168 offset:3584
	s_waitcnt lgkmcnt(12)
	v_mfma_f32_32x32x16_bf16 v[16:31], v[216:219], v[152:155], v[16:31]
	ds_read_b64_tr_b16 v[140:141], v168 offset:5632
	ds_read_b64_tr_b16 v[142:143], v168 offset:7680
	s_waitcnt lgkmcnt(12)
	v_mfma_f32_32x32x16_bf16 v[16:31], v[220:223], v[160:163], v[16:31]
	ds_read_b64_tr_b16 v[152:153], v168 offset:9728
	ds_read_b64_tr_b16 v[154:155], v168 offset:11776
	s_waitcnt lgkmcnt(12)
	v_mfma_f32_32x32x16_bf16 v[32:47], v[208:211], v[84:87], v[32:47]
	ds_read_b64_tr_b16 v[160:161], v168 offset:13824
	ds_read_b64_tr_b16 v[162:163], v168 offset:15872
	v_xor_b32_e32 v168, 0x4000, v168
	s_waitcnt lgkmcnt(12)
	v_mfma_f32_32x32x16_bf16 v[32:47], v[212:215], v[88:91], v[32:47]
	s_waitcnt lgkmcnt(10)
	v_mfma_f32_32x32x16_bf16 v[32:47], v[216:219], v[92:95], v[32:47]
	s_waitcnt lgkmcnt(8)
	v_mfma_f32_32x32x16_bf16 v[32:47], v[220:223], v[128:131], v[32:47]
	s_waitcnt lgkmcnt(6)
	v_mfma_f32_32x32x16_bf16 v[48:63], v[208:211], v[132:135], v[48:63]
	s_waitcnt lgkmcnt(4)
	v_mfma_f32_32x32x16_bf16 v[48:63], v[212:215], v[140:143], v[48:63]
	s_waitcnt lgkmcnt(2)
	v_mfma_f32_32x32x16_bf16 v[48:63], v[216:219], v[152:155], v[48:63]
	s_waitcnt lgkmcnt(0)
	v_mfma_f32_32x32x16_bf16 v[48:63], v[220:223], v[160:163], v[48:63]
	s_barrier
	s_barrier
	s_branch .Lat_done
; #define SBAR() __builtin_amdgcn_sched_barrier(0)
; #define KFRAG(d0, row) (*reinterpret_cast<const bf16x8*>(Ks + KSWZ((row), (half * 64 + (d0) * 16 + hi * 8) * 2)))
; __device__ __forceinline__ void qkt(f32x16& p0, f32x16& p1, const char* Ks, const bf16x8* qr, float c0, int r32, int hi, int half) {
;     ...
;     bf16x8 a0 = KFRAG(0, r32), a1 = KFRAG(0, 32 + r32), b0 = KFRAG(1, r32), b1 = KFRAG(1, 32 + r32);
;     SBAR();
; #pragma unroll
;     for (int r = 0; r < 16; ++r) { p0[r] = c0; p1[r] = c0; }
;     SBAR();
;     p0 = __builtin_amdgcn_mfma_f32_32x32x16_bf16(a0, qr[0], p0, 0, 0, 0); p1 = __builtin_amdgcn_mfma_f32_32x32x16_bf16(a1, qr[0], p1, 0, 0, 0);
;     a0 = KFRAG(2, r32); a1 = KFRAG(2, 32 + r32);
;     SBAR();
;     p0 = __builtin_amdgcn_mfma_f32_32x32x16_bf16(b0, qr[1], p0, 0, 0, 0); p1 = __builtin_amdgcn_mfma_f32_32x32x16_bf16(b1, qr[1], p1, 0, 0, 0);
;     b0 = KFRAG(3, r32); b1 = KFRAG(3, 32 + r32);
;     SBAR();
;     p0 = __builtin_amdgcn_mfma_f32_32x32x16_bf16(a0, qr[2], p0, 0, 0, 0); p1 = __builtin_amdgcn_mfma_f32_32x32x16_bf16(a1, qr[2], p1, 0, 0, 0);
;     p0 = __builtin_amdgcn_mfma_f32_32x32x16_bf16(b0, qr[3], p0, 0, 0, 0); p1 = __builtin_amdgcn_mfma_f32_32x32x16_bf16(b1, qr[3], p1, 0, 0, 0);
; template <int MODE>
; __device__ __forceinline__ void attn_unit(const UnitArgs& A, char* lds, const int wave_) {
;     ...
;     auto zone_of = [&](int t) -> int { const int k0 = 64 * t, qw0 = A.q0 + 32 * qb; return (k0 + 63 - qw0 <= -128) ? 0 : ((k0 - qw0 - 31 >= 128) ? 2 : 1); };
;     ...
;     auto post = [&](f32x16& p0, f32x16& p1, int t) {
;         SBAR();
;         if (MODE == 0) {
;             if (zone_of(t) == 1) { const int k0 = 64 * t, qw0 = A.q0 + 32 * qb;
;                 const float* b = lutA + A.h * LUTA_STRIDE + (k0 - qw0 - r32 + 4 * hi + 320);
; #pragma unroll
;                 for (int r = 0; r < 16; ++r) { const int c = (r & 3) + 8 * (r >> 2); p0[r] += b[c]; p1[r] += b[32 + c]; } }
.Lat_g1:
	s_barrier
	ds_read_b128 v[224:227], v164
	ds_read_b128 v[228:231], v164 offset:8192
	ds_read_b128 v[232:235], v165
	ds_read_b128 v[236:239], v165 offset:8192
	ds_read_b128 v[240:243], v166
	ds_read_b128 v[244:247], v166 offset:8192
	ds_read_b128 v[248:251], v167
	ds_read_b128 v[188:191], v167 offset:8192
	v_xor_b32_e32 v164, 0x4000, v164
	v_xor_b32_e32 v165, 0x4000, v165
	v_xor_b32_e32 v166, 0x4000, v166
	v_xor_b32_e32 v167, 0x4000, v167
	s_waitcnt lgkmcnt(7)
	v_mfma_f32_32x32x16_bf16 v[112:127], v[224:227], v[108:111], v[68:83]
	s_waitcnt lgkmcnt(6)
	v_mfma_f32_32x32x16_bf16 v[192:207], v[228:231], v[108:111], v[68:83]
	s_waitcnt lgkmcnt(5)
	v_mfma_f32_32x32x16_bf16 v[112:127], v[232:235], v[104:107], v[112:127]
	s_waitcnt lgkmcnt(4)
	v_mfma_f32_32x32x16_bf16 v[192:207], v[236:239], v[104:107], v[192:207]
	s_waitcnt lgkmcnt(3)
	v_mfma_f32_32x32x16_bf16 v[112:127], v[240:243], v[100:103], v[112:127]
	s_waitcnt lgkmcnt(2)
	v_mfma_f32_32x32x16_bf16 v[192:207], v[244:247], v[100:103], v[192:207]
	s_waitcnt lgkmcnt(1)
	v_mfma_f32_32x32x16_bf16 v[112:127], v[248:251], v[96:99], v[112:127]
	s_waitcnt lgkmcnt(0)
	v_mfma_f32_32x32x16_bf16 v[192:207], v[188:191], v[96:99], v[192:207]
	s_nop 7
	s_nop 3
	s_barrier
.Lat_g1_loop:
	s_mov_b32 m0, s31
	s_add_u32 s101, s31, 0x2000
	global_load_lds_dwordx4 v169, s[24:25]
	s_mov_b32 m0, s101
	s_xor_b32 s31, s31, 0x4000
	global_load_lds_dwordx4 v170, s[24:25]
	s_mov_b32 m0, s33
	s_add_u32 s101, s33, 0x2000
	global_load_lds_dwordx4 v171, s[26:27]
	s_mov_b32 m0, s101
	s_xor_b32 s33, s33, 0x4000
	global_load_lds_dwordx4 v172, s[26:27]
	s_add_u32 s24, s24, 0x50000
	s_addc_u32 s25, s25, 0
	s_add_u32 s26, s26, 0x50000
	s_addc_u32 s27, s27, 0
	s_cmp_gt_i32 s23, s29
	s_cselect_b32 s101, 1, 0
	s_cmp_lt_i32 s23, s30
	s_cselect_b32 s6, 1, 0
	s_and_b32 s101, s101, s6
	s_cbranch_scc0 .Lat_far_g1l
	v_add_u32_e32 v181, s35, v174
	ds_read2_b32 v[224:225], v181 offset0:0 offset1:1
	ds_read2_b32 v[226:227], v181 offset0:2 offset1:3
	ds_read2_b32 v[228:229], v181 offset0:8 offset1:9
	ds_read2_b32 v[230:231], v181 offset0:10 offset1:11
	ds_read2_b32 v[232:233], v181 offset0:16 offset1:17
	ds_read2_b32 v[234:235], v181 offset0:18 offset1:19
	ds_read2_b32 v[236:237], v181 offset0:24 offset1:25
	ds_read2_b32 v[238:239], v181 offset0:26 offset1:27
	s_waitcnt lgkmcnt(4)
	ds_read2_b32 v[240:241], v181 offset0:32 offset1:33
	ds_read2_b32 v[242:243], v181 offset0:34 offset1:35
	ds_read2_b32 v[244:245], v181 offset0:40 offset1:41
	ds_read2_b32 v[246:247], v181 offset0:42 offset1:43
	ds_read2_b32 v[248:249], v181 offset0:48 offset1:49
	ds_read2_b32 v[250:251], v181 offset0:50 offset1:51
	ds_read2_b32 v[188:189], v181 offset0:56 offset1:57
	ds_read2_b32 v[190:191], v181 offset0:58 offset1:59
	s_waitcnt lgkmcnt(8)
	v_add_f32_e32 v112, v112, v224
	v_add_f32_e32 v113, v113, v225
	v_add_f32_e32 v114, v114, v226
	v_add_f32_e32 v115, v115, v227
	v_add_f32_e32 v116, v116, v228
	v_add_f32_e32 v117, v117, v229
	v_add_f32_e32 v118, v118, v230
	v_add_f32_e32 v119, v119, v231
	v_add_f32_e32 v120, v120, v232
	v_add_f32_e32 v121, v121, v233
	v_add_f32_e32 v122, v122, v234
	v_add_f32_e32 v123, v123, v235
	v_add_f32_e32 v124, v124, v236
	v_add_f32_e32 v125, v125, v237
	v_add_f32_e32 v126, v126, v238
	v_add_f32_e32 v127, v127, v239
	s_waitcnt lgkmcnt(0)
	v_add_f32_e32 v192, v192, v240
	v_add_f32_e32 v193, v193, v241
	v_add_f32_e32 v194, v194, v242
	v_add_f32_e32 v195, v195, v243
	v_add_f32_e32 v196, v196, v244
	v_add_f32_e32 v197, v197, v245
	v_add_f32_e32 v198, v198, v246
	v_add_f32_e32 v199, v199, v247
	v_add_f32_e32 v200, v200, v248
	v_add_f32_e32 v201, v201, v249
	v_add_f32_e32 v202, v202, v250
	v_add_f32_e32 v203, v203, v251
	v_add_f32_e32 v204, v204, v188
	v_add_f32_e32 v205, v205, v189
	v_add_f32_e32 v206, v206, v190
	v_add_f32_e32 v207, v207, v191

; #define SBAR() __builtin_amdgcn_sched_barrier(0)
; __device__ __forceinline__ void qkt(f32x16& p0, f32x16& p1, const char* Ks, const bf16x8* qr, float c0, int r32, int hi, int half) {
;     ...
;     bf16x8 a0 = KFRAG(0, r32), a1 = KFRAG(0, 32 + r32), b0 = KFRAG(1, r32), b1 = KFRAG(1, 32 + r32);
;     SBAR();
; #pragma unroll
;     for (int r = 0; r < 16; ++r) { p0[r] = c0; p1[r] = c0; }
;     SBAR();
;     p0 = __builtin_amdgcn_mfma_f32_32x32x16_bf16(a0, qr[0], p0, 0, 0, 0); p1 = __builtin_amdgcn_mfma_f32_32x32x16_bf16(a1, qr[0], p1, 0, 0, 0);
;     a0 = KFRAG(2, r32); a1 = KFRAG(2, 32 + r32);
;     SBAR();
;     p0 = __builtin_amdgcn_mfma_f32_32x32x16_bf16(b0, qr[1], p0, 0, 0, 0); p1 = __builtin_amdgcn_mfma_f32_32x32x16_bf16(b1, qr[1], p1, 0, 0, 0);
;     b0 = KFRAG(3, r32); b1 = KFRAG(3, 32 + r32);
;     SBAR();
;     p0 = __builtin_amdgcn_mfma_f32_32x32x16_bf16(a0, qr[2], p0, 0, 0, 0); p1 = __builtin_amdgcn_mfma_f32_32x32x16_bf16(a1, qr[2], p1, 0, 0, 0);
;     p0 = __builtin_amdgcn_mfma_f32_32x32x16_bf16(b0, qr[3], p0, 0, 0, 0); p1 = __builtin_amdgcn_mfma_f32_32x32x16_bf16(b1, qr[3], p1, 0, 0, 0);
;     ...
; }
; __device__ __forceinline__ int v_st(int k, int c) { const int kk = (k & ~0xC) | ((k & 4) << 1) | ((k & 8) >> 1); return ((kk >> 3) * 4 + (c >> 5)) * 512 + ((kk & 7) * 32 + (c & 31)) * 2; }
; __device__ __forceinline__ int v_rd_base(int lane) { return ((lane & 3) << 3) | (((lane >> 2) & 3) << 6) | (((lane >> 4) & 1) << 5) | (((lane >> 5) & 1) << 8); }
; template <int OFF> __device__ __forceinline__ s16x4 tr_read(int vb) { s16x4 r; asm volatile("ds_read_b64_tr_b16 %0, %1 offset:%2" : "=&v"(r) : "v"(vb), "i"(OFF) : "memory"); return r; }
; template <int NB> __device__ __forceinline__ void pv_blocks(f32x16* o, int vb, bf16x8 pa0, bf16x8 pa1, bf16x8 pa2, bf16x8 pa3, f32x16& pe0, f32x16& pe1) {
;     s16x4 x[8], y[8];
;     ...
;     PVLOAD(0, x); PVWAIT();
;     if (NB == 4) {
;         PVLOAD(1, y); SBAR(); PVMMA(o[0], x); PVEXP(pe0, 0, 8); SBAR(); PVWAIT();
;         PVLOAD(2, x); SBAR(); PVMMA(o[1], y); PVEXP(pe0, 8, 8); SBAR(); PVWAIT();
;         PVLOAD(3, y); SBAR(); PVMMA(o[2], x); PVEXP(pe1, 0, 8); SBAR(); PVWAIT();
;         PVMMA(o[3], y); PVEXP(pe1, 8, 8);
;     } else {
;         PVLOAD(1, y); SBAR(); PVMMA(o[0], x); PVEXP(pe0, 0, 16); SBAR(); PVWAIT();
;         PVMMA(o[1], y); PVEXP(pe1, 0, 16);
;     }
;     ...
; }
.Lat_c0same_g1l:
	ds_read_b128 v[224:227], v164
	ds_read_b128 v[228:231], v164 offset:8192
	ds_read_b128 v[232:235], v165
	ds_read_b128 v[236:239], v165 offset:8192
	ds_read_b128 v[240:243], v166
	ds_read_b128 v[244:247], v166 offset:8192
	ds_read_b128 v[248:251], v167
	ds_read_b128 v[188:191], v167 offset:8192
	v_xor_b32_e32 v164, 0x4000, v164
	v_xor_b32_e32 v165, 0x4000, v165
	v_xor_b32_e32 v166, 0x4000, v166
	v_xor_b32_e32 v167, 0x4000, v167
	s_barrier
	s_waitcnt lgkmcnt(7)
	v_mfma_f32_32x32x16_bf16 v[112:127], v[224:227], v[108:111], v[68:83]
	s_waitcnt lgkmcnt(6)
	v_mfma_f32_32x32x16_bf16 v[192:207], v[228:231], v[108:111], v[68:83]
	ds_read_b64_tr_b16 v[84:85], v168 offset:0
	ds_read_b64_tr_b16 v[86:87], v168 offset:2048
	s_waitcnt lgkmcnt(7)
	v_mfma_f32_32x32x16_bf16 v[112:127], v[232:235], v[104:107], v[112:127]
	ds_read_b64_tr_b16 v[88:89], v168 offset:4096
	ds_read_b64_tr_b16 v[90:91], v168 offset:6144
	s_waitcnt lgkmcnt(8)
	v_mfma_f32_32x32x16_bf16 v[192:207], v[236:239], v[104:107], v[192:207]
	ds_read_b64_tr_b16 v[92:93], v168 offset:8192
	ds_read_b64_tr_b16 v[94:95], v168 offset:10240
	s_waitcnt lgkmcnt(9)
	v_mfma_f32_32x32x16_bf16 v[112:127], v[240:243], v[100:103], v[112:127]
	ds_read_b64_tr_b16 v[128:129], v168 offset:12288
	ds_read_b64_tr_b16 v[130:131], v168 offset:14336
	s_waitcnt lgkmcnt(10)
	v_mfma_f32_32x32x16_bf16 v[192:207], v[244:247], v[100:103], v[192:207]
	ds_read_b64_tr_b16 v[132:133], v168 offset:512
	ds_read_b64_tr_b16 v[134:135], v168 offset:2560
	s_waitcnt lgkmcnt(11)
	v_mfma_f32_32x32x16_bf16 v[112:127], v[248:251], v[96:99], v[112:127]
	ds_read_b64_tr_b16 v[140:141], v168 offset:4608
	ds_read_b64_tr_b16 v[142:143], v168 offset:6656
	s_waitcnt lgkmcnt(12)
	v_mfma_f32_32x32x16_bf16 v[192:207], v[188:191], v[96:99], v[192:207]
	ds_read_b64_tr_b16 v[152:153], v168 offset:8704
	ds_read_b64_tr_b16 v[154:155], v168 offset:10752
	s_waitcnt lgkmcnt(12)
	v_mfma_f32_32x32x16_bf16 v[0:15], v[208:211], v[84:87], v[0:15]
	ds_read_b64_tr_b16 v[160:161], v168 offset:12800
	ds_read_b64_tr_b16 v[162:163], v168 offset:14848
	s_waitcnt lgkmcnt(12)
	v_mfma_f32_32x32x16_bf16 v[0:15], v[212:215], v[88:91], v[0:15]
	ds_read_b64_tr_b16 v[84:85], v168 offset:1024
	ds_read_b64_tr_b16 v[86:87], v168 offset:3072
	s_waitcnt lgkmcnt(12)
	v_mfma_f32_32x32x16_bf16 v[0:15], v[216:219], v[92:95], v[0:15]
	ds_read_b64_tr_b16 v[88:89], v168 offset:5120
	ds_read_b64_tr_b16 v[90:91], v168 offset:7168
	s_waitcnt lgkmcnt(12)
	v_mfma_f32_32x32x16_bf16 v[0:15], v[220:223], v[128:131], v[0:15]
	ds_read_b64_tr_b16 v[92:93], v168 offset:9216
	ds_read_b64_tr_b16 v[94:95], v168 offset:11264
	s_waitcnt lgkmcnt(12)
	v_mfma_f32_32x32x16_bf16 v[16:31], v[208:211], v[132:135], v[16:31]
	ds_read_b64_tr_b16 v[128:129], v168 offset:13312
	ds_read_b64_tr_b16 v[130:131], v168 offset:15360
	s_waitcnt lgkmcnt(12)
	v_mfma_f32_32x32x16_bf16 v[16:31], v[212:215], v[140:143], v[16:31]
	ds_read_b64_tr_b16 v[132:133], v168 offset:1536
	ds_read_b64_tr_b16 v[134:135], v168 offset:3584
	s_waitcnt lgkmcnt(12)
	v_mfma_f32_32x32x16_bf16 v[16:31], v[216:219], v[152:155], v[16:31]
	ds_read_b64_tr_b16 v[140:141], v168 offset:5632
	ds_read_b64_tr_b16 v[142:143], v168 offset:7680
	s_waitcnt lgkmcnt(12)
	v_mfma_f32_32x32x16_bf16 v[16:31], v[220:223], v[160:163], v[16:31]
	ds_read_b64_tr_b16 v[152:153], v168 offset:9728
	ds_read_b64_tr_b16 v[154:155], v168 offset:11776
	s_waitcnt lgkmcnt(12)
	v_mfma_f32_32x32x16_bf16 v[32:47], v[208:211], v[84:87], v[32:47]
	ds_read_b64_tr_b16 v[160:161], v168 offset:13824
	ds_read_b64_tr_b16 v[162:163], v168 offset:15872
	v_xor_b32_e32 v168, 0x4000, v168
	s_waitcnt lgkmcnt(12)
	v_mfma_f32_32x32x16_bf16 v[32:47], v[212:215], v[88:91], v[32:47]
	s_waitcnt lgkmcnt(10)
	v_mfma_f32_32x32x16_bf16 v[32:47], v[216:219], v[92:95], v[32:47]
	s_waitcnt lgkmcnt(8)
	v_mfma_f32_32x32x16_bf16 v[32:47], v[220:223], v[128:131], v[32:47]
	s_waitcnt lgkmcnt(6)
	v_mfma_f32_32x32x16_bf16 v[48:63], v[208:211], v[132:135], v[48:63]
	s_waitcnt lgkmcnt(4)
	v_mfma_f32_32x32x16_bf16 v[48:63], v[212:215], v[140:143], v[48:63]
	s_waitcnt lgkmcnt(2)
	v_mfma_f32_32x32x16_bf16 v[48:63], v[216:219], v[152:155], v[48:63]
	s_waitcnt lgkmcnt(0)
	v_mfma_f32_32x32x16_bf16 v[48:63], v[220:223], v[160:163], v[48:63]
	s_add_i32 s34, s34, 1
	s_add_i32 s23, s23, 64
	s_addk_i32 s35, 0x100
	s_waitcnt vmcnt(0)
	s_barrier
	s_cmp_lt_u32 s34, s20
	s_cbranch_scc1 .Lat_g1_loop
	s_cmp_gt_i32 s23, s29
	s_cselect_b32 s101, 1, 0
	s_cmp_lt_i32 s23, s30
	s_cselect_b32 s6, 1, 0
	s_and_b32 s101, s101, s6
	s_cbranch_scc0 .Lat_far_g1p
	v_add_u32_e32 v181, s35, v174
	ds_read2_b32 v[224:225], v181 offset0:0 offset1:1
	ds_read2_b32 v[226:227], v181 offset0:2 offset1:3
	ds_read2_b32 v[228:229], v181 offset0:8 offset1:9
	ds_read2_b32 v[230:231], v181 offset0:10 offset1:11
	ds_read2_b32 v[232:233], v181 offset0:16 offset1:17
	ds_read2_b32 v[234:235], v181 offset0:18 offset1:19
	ds_read2_b32 v[236:237], v181 offset0:24 offset1:25
	ds_read2_b32 v[238:239], v181 offset0:26 offset1:27
	s_waitcnt lgkmcnt(4)
	ds_read2_b32 v[240:241], v181 offset0:32 offset1:33
	ds_read2_b32 v[242:243], v181 offset0:34 offset1:35
	ds_read2_b32 v[244:245], v181 offset0:40 offset1:41
	ds_read2_b32 v[246:247], v181 offset0:42 offset1:43
	ds_read2_b32 v[248:249], v181 offset0:48 offset1:49
	ds_read2_b32 v[250:251], v181 offset0:50 offset1:51
	ds_read2_b32 v[188:189], v181 offset0:56 offset1:57
	ds_read2_b32 v[190:191], v181 offset0:58 offset1:59
	s_waitcnt lgkmcnt(8)
	v_add_f32_e32 v112, v112, v224
	v_add_f32_e32 v113, v113, v225
	v_add_f32_e32 v114, v114, v226
	v_add_f32_e32 v115, v115, v227
	v_add_f32_e32 v116, v116, v228
	v_add_f32_e32 v117, v117, v229
	v_add_f32_e32 v118, v118, v230
	v_add_f32_e32 v119, v119, v231
	v_add_f32_e32 v120, v120, v232
	v_add_f32_e32 v121, v121, v233
	v_add_f32_e32 v122, v122, v234
	v_add_f32_e32 v123, v123, v235
	v_add_f32_e32 v124, v124, v236
	v_add_f32_e32 v125, v125, v237
	v_add_f32_e32 v126, v126, v238
	v_add_f32_e32 v127, v127, v239
	s_waitcnt lgkmcnt(0)
	v_add_f32_e32 v192, v192, v240
	v_add_f32_e32 v193, v193, v241
	v_add_f32_e32 v194, v194, v242
	v_add_f32_e32 v195, v195, v243
	v_add_f32_e32 v196, v196, v244
	v_add_f32_e32 v197, v197, v245
	v_add_f32_e32 v198, v198, v246
	v_add_f32_e32 v199, v199, v247
	v_add_f32_e32 v200, v200, v248
	v_add_f32_e32 v201, v201, v249
	v_add_f32_e32 v202, v202, v250
	v_add_f32_e32 v203, v203, v251
	v_add_f32_e32 v204, v204, v188
	v_add_f32_e32 v205, v205, v189
	v_add_f32_e32 v206, v206, v190
	v_add_f32_e32 v207, v207, v191
; #define SBAR() __builtin_amdgcn_sched_barrier(0)
; #define PVLOAD(D0, X) do { X[0] = tr_read<v_rd_off(D0, 0, 0)>(vb); X[1] = tr_read<v_rd_off(D0, 0, 1)>(vb); X[2] = tr_read<v_rd_off(D0, 1, 0)>(vb); X[3] = tr_read<v_rd_off(D0, 1, 1)>(vb); \
;     X[4] = tr_read<v_rd_off(D0, 2, 0)>(vb); X[5] = tr_read<v_rd_off(D0, 2, 1)>(vb); X[6] = tr_read<v_rd_off(D0, 3, 0)>(vb); X[7] = tr_read<v_rd_off(D0, 3, 1)>(vb); } while (0)
; #define PVMMA(OD, X) do { OD = __builtin_amdgcn_mfma_f32_32x32x16_bf16(pa0, PVPK(X[0], X[1]), OD, 0, 0, 0); OD = __builtin_amdgcn_mfma_f32_32x32x16_bf16(pa1, PVPK(X[2], X[3]), OD, 0, 0, 0); \
;     OD = __builtin_amdgcn_mfma_f32_32x32x16_bf16(pa2, PVPK(X[4], X[5]), OD, 0, 0, 0); OD = __builtin_amdgcn_mfma_f32_32x32x16_bf16(pa3, PVPK(X[6], X[7]), OD, 0, 0, 0); } while (0)
; #define PVWAIT() do { asm volatile("s_waitcnt lgkmcnt(0)" ::: "memory"); SBAR(); } while (0)
; #define PVEXP(P, B, N) do { _Pragma("unroll") for (int r = (B); r < (B) + (N); ++r) P[r] = __builtin_amdgcn_exp2f(P[r]); } while (0)
; __device__ __forceinline__ void expHalf(f32x16& p0) {
; #pragma unroll
;     for (int r = 0; r < 16; ++r) p0[r] = __builtin_amdgcn_exp2f(p0[r]);
; }
; __device__ __forceinline__ void finishSM(f32x16& p0, f32x16& p1, float& l_reg, bf16x8& pa0, bf16x8& pa1, bf16x8& pa2, bf16x8& pa3) {
;     float ps = 0;
; #pragma unroll
;     for (int r = 0; r < 16; ++r) ps += p0[r];
; #pragma unroll
;     for (int r = 0; r < 16; ++r) ps += p1[r];
;     l_reg += ps;
;     ...
;     PK4(p0, 0, pa0); PK4(p0, 8, pa1); PK4(p1, 0, pa2); PK4(p1, 8, pa3);
;     ...
; }
; template <int NB> __device__ __forceinline__ void pv_blocks(f32x16* o, int vb, bf16x8 pa0, bf16x8 pa1, bf16x8 pa2, bf16x8 pa3, f32x16& pe0, f32x16& pe1) {
;     s16x4 x[8], y[8];
;     ...
;     PVLOAD(0, x); PVWAIT();
;     if (NB == 4) {
;         PVLOAD(1, y); SBAR(); PVMMA(o[0], x); PVEXP(pe0, 0, 8); SBAR(); PVWAIT();
;         PVLOAD(2, x); SBAR(); PVMMA(o[1], y); PVEXP(pe0, 8, 8); SBAR(); PVWAIT();
;         PVLOAD(3, y); SBAR(); PVMMA(o[2], x); PVEXP(pe1, 0, 8); SBAR(); PVWAIT();
;         PVMMA(o[3], y); PVEXP(pe1, 8, 8);
;     } else {
;         PVLOAD(1, y); SBAR(); PVMMA(o[0], x); PVEXP(pe0, 0, 16); SBAR(); PVWAIT();
;         PVMMA(o[1], y); PVEXP(pe1, 0, 16);
;     }
;     ...
; }
.Lat_far_g1p:
	v_exp_f32_e32 v112, v112
	v_exp_f32_e32 v113, v113
	v_exp_f32_e32 v114, v114
	v_exp_f32_e32 v115, v115
	v_exp_f32_e32 v116, v116
	v_exp_f32_e32 v117, v117
	v_exp_f32_e32 v118, v118
	v_exp_f32_e32 v119, v119
	v_exp_f32_e32 v120, v120
	v_exp_f32_e32 v121, v121
	v_exp_f32_e32 v122, v122
	v_exp_f32_e32 v123, v123
	v_exp_f32_e32 v124, v124
	v_exp_f32_e32 v125, v125
	v_exp_f32_e32 v126, v126
	v_exp_f32_e32 v127, v127
	v_exp_f32_e32 v192, v192
	v_add_f32_e32 v64, v64, v112
	v_exp_f32_e32 v193, v193
	v_add_f32_e32 v65, v65, v113
	v_exp_f32_e32 v194, v194
	v_add_f32_e32 v66, v66, v114
	v_exp_f32_e32 v195, v195
	v_add_f32_e32 v67, v67, v115
	v_exp_f32_e32 v196, v196
	v_add_f32_e32 v64, v64, v116
	v_exp_f32_e32 v197, v197
	v_add_f32_e32 v65, v65, v117
	v_exp_f32_e32 v198, v198
	v_add_f32_e32 v66, v66, v118
	v_exp_f32_e32 v199, v199
	v_add_f32_e32 v67, v67, v119
	v_exp_f32_e32 v200, v200
	v_add_f32_e32 v64, v64, v120
	v_exp_f32_e32 v201, v201
	v_add_f32_e32 v65, v65, v121
	v_exp_f32_e32 v202, v202
	v_add_f32_e32 v66, v66, v122
	v_exp_f32_e32 v203, v203
	v_add_f32_e32 v67, v67, v123
	v_exp_f32_e32 v204, v204
	v_add_f32_e32 v64, v64, v124
	v_exp_f32_e32 v205, v205
	v_add_f32_e32 v65, v65, v125
	v_exp_f32_e32 v206, v206
	v_add_f32_e32 v66, v66, v126
	v_exp_f32_e32 v207, v207
	v_add_f32_e32 v67, v67, v127
	v_cvt_pk_bf16_f32 v208, v112, v113
	v_cvt_pk_bf16_f32 v209, v114, v115
	v_cvt_pk_bf16_f32 v210, v116, v117
	v_cvt_pk_bf16_f32 v211, v118, v119
	v_cvt_pk_bf16_f32 v212, v120, v121
	v_cvt_pk_bf16_f32 v213, v122, v123
	v_cvt_pk_bf16_f32 v214, v124, v125
	v_cvt_pk_bf16_f32 v215, v126, v127
	v_add_f32_e32 v64, v64, v192
	v_add_f32_e32 v65, v65, v193
	v_add_f32_e32 v66, v66, v194
	v_add_f32_e32 v67, v67, v195
	v_add_f32_e32 v64, v64, v196
	v_add_f32_e32 v65, v65, v197
	v_add_f32_e32 v66, v66, v198
	v_add_f32_e32 v67, v67, v199
	v_permlane32_swap_b32_e32 v208, v210
	v_permlane32_swap_b32_e32 v209, v211
	v_permlane32_swap_b32_e32 v212, v214
	v_permlane32_swap_b32_e32 v213, v215
	v_add_f32_e32 v64, v64, v200
	v_add_f32_e32 v65, v65, v201
	v_add_f32_e32 v66, v66, v202
	v_add_f32_e32 v67, v67, v203
	v_add_f32_e32 v64, v64, v204
	v_add_f32_e32 v65, v65, v205
	v_add_f32_e32 v66, v66, v206
	v_add_f32_e32 v67, v67, v207
	v_cvt_pk_bf16_f32 v216, v192, v193
	v_cvt_pk_bf16_f32 v217, v194, v195
	v_cvt_pk_bf16_f32 v218, v196, v197
	v_cvt_pk_bf16_f32 v219, v198, v199
	v_cvt_pk_bf16_f32 v220, v200, v201
	v_cvt_pk_bf16_f32 v221, v202, v203
	v_cvt_pk_bf16_f32 v222, v204, v205
	v_cvt_pk_bf16_f32 v223, v206, v207
	s_nop 1
	v_permlane32_swap_b32_e32 v216, v218
	v_permlane32_swap_b32_e32 v217, v219
	v_permlane32_swap_b32_e32 v220, v222
	v_permlane32_swap_b32_e32 v221, v223
	s_barrier
	ds_read_b64_tr_b16 v[84:85], v168 offset:0
	ds_read_b64_tr_b16 v[86:87], v168 offset:2048
	ds_read_b64_tr_b16 v[88:89], v168 offset:4096
	ds_read_b64_tr_b16 v[90:91], v168 offset:6144
	ds_read_b64_tr_b16 v[92:93], v168 offset:8192
	ds_read_b64_tr_b16 v[94:95], v168 offset:10240
	ds_read_b64_tr_b16 v[128:129], v168 offset:12288
	ds_read_b64_tr_b16 v[130:131], v168 offset:14336
	ds_read_b64_tr_b16 v[132:133], v168 offset:512
	ds_read_b64_tr_b16 v[134:135], v168 offset:2560
	ds_read_b64_tr_b16 v[140:141], v168 offset:4608
	ds_read_b64_tr_b16 v[142:143], v168 offset:6656
	ds_read_b64_tr_b16 v[152:153], v168 offset:8704
	ds_read_b64_tr_b16 v[154:155], v168 offset:10752
	s_waitcnt lgkmcnt(12)
	v_mfma_f32_32x32x16_bf16 v[0:15], v[208:211], v[84:87], v[0:15]
	ds_read_b64_tr_b16 v[160:161], v168 offset:12800
	ds_read_b64_tr_b16 v[162:163], v168 offset:14848
	s_waitcnt lgkmcnt(12)
	v_mfma_f32_32x32x16_bf16 v[0:15], v[212:215], v[88:91], v[0:15]
	ds_read_b64_tr_b16 v[84:85], v168 offset:1024
	ds_read_b64_tr_b16 v[86:87], v168 offset:3072
	s_waitcnt lgkmcnt(12)
	v_mfma_f32_32x32x16_bf16 v[0:15], v[216:219], v[92:95], v[0:15]
	ds_read_b64_tr_b16 v[88:89], v168 offset:5120
	ds_read_b64_tr_b16 v[90:91], v168 offset:7168
	s_waitcnt lgkmcnt(12)
	v_mfma_f32_32x32x16_bf16 v[0:15], v[220:223], v[128:131], v[0:15]
	ds_read_b64_tr_b16 v[92:93], v168 offset:9216
	ds_read_b64_tr_b16 v[94:95], v168 offset:11264
	s_waitcnt lgkmcnt(12)
	v_mfma_f32_32x32x16_bf16 v[16:31], v[208:211], v[132:135], v[16:31]
	ds_read_b64_tr_b16 v[128:129], v168 offset:13312
	ds_read_b64_tr_b16 v[130:131], v168 offset:15360
	s_waitcnt lgkmcnt(12)
	v_mfma_f32_32x32x16_bf16 v[16:31], v[212:215], v[140:143], v[16:31]
	ds_read_b64_tr_b16 v[132:133], v168 offset:1536
	ds_read_b64_tr_b16 v[134:135], v168 offset:3584
	s_waitcnt lgkmcnt(12)
	v_mfma_f32_32x32x16_bf16 v[16:31], v[216:219], v[152:155], v[16:31]
	ds_read_b64_tr_b16 v[140:141], v168 offset:5632
	ds_read_b64_tr_b16 v[142:143], v168 offset:7680
	s_waitcnt lgkmcnt(12)
	v_mfma_f32_32x32x16_bf16 v[16:31], v[220:223], v[160:163], v[16:31]
	ds_read_b64_tr_b16 v[152:153], v168 offset:9728
	ds_read_b64_tr_b16 v[154:155], v168 offset:11776
	s_waitcnt lgkmcnt(12)
	v_mfma_f32_32x32x16_bf16 v[32:47], v[208:211], v[84:87], v[32:47]
	ds_read_b64_tr_b16 v[160:161], v168 offset:13824
	ds_read_b64_tr_b16 v[162:163], v168 offset:15872
	v_xor_b32_e32 v168, 0x4000, v168
	s_waitcnt lgkmcnt(12)
	v_mfma_f32_32x32x16_bf16 v[32:47], v[212:215], v[88:91], v[32:47]
	s_waitcnt lgkmcnt(10)
	v_mfma_f32_32x32x16_bf16 v[32:47], v[216:219], v[92:95], v[32:47]
	s_waitcnt lgkmcnt(8)
	v_mfma_f32_32x32x16_bf16 v[32:47], v[220:223], v[128:131], v[32:47]
	s_waitcnt lgkmcnt(6)
	v_mfma_f32_32x32x16_bf16 v[48:63], v[208:211], v[132:135], v[48:63]
	s_waitcnt lgkmcnt(4)
	v_mfma_f32_32x32x16_bf16 v[48:63], v[212:215], v[140:143], v[48:63]
	s_waitcnt lgkmcnt(2)
	v_mfma_f32_32x32x16_bf16 v[48:63], v[216:219], v[152:155], v[48:63]
	s_waitcnt lgkmcnt(0)
	v_mfma_f32_32x32x16_bf16 v[48:63], v[220:223], v[160:163], v[48:63]
	s_waitcnt vmcnt(0)
	s_barrier
; __device__ __forceinline__ int crow(int r, int hi) { return (r & 3) + 8 * (r >> 2) + 4 * hi; }
; template <int MODE>
; __device__ __forceinline__ void attn_unit(const UnitArgs& A, char* lds, const int wave_) {
;     ...
;     { auto rr = __builtin_amdgcn_permlane32_swap(__float_as_uint(l_reg), __float_as_uint(l_reg), false, false); l_reg = __uint_as_float(rr[0]) + __uint_as_float(rr[1]); }
;     if (hi == 0) li_l[r32] = l_reg; asm volatile("s_waitcnt lgkmcnt(0)" ::: "memory");
;     float rli[16];
; #pragma unroll
;     for (int r = 0; r < 16; ++r) rli[r] = __builtin_amdgcn_rcpf(li_l[crow(r, hi)]);
;     if (MODE == 0) {
;         __syncthreads();
;         float* pb = (float*)lds + qb * (32 * 128);
;         if (half == 1) {
; #pragma unroll
;             for (int r = 0; r < 16; ++r)
; #pragma unroll
;                 for (int d0 = 0; d0 < 4; ++d0) pb[crow(r, hi) * 128 + d0 * 32 + r32] = o[d0][r] * rli[r] * A.lam;
.Lat_done:
	v_add_f32_e32 v64, v64, v65
	v_add_f32_e32 v66, v66, v67
	s_and_b32 s6, s0, 0x3fffffc0
	s_lshl_b32 s6, s6, 2
	s_add_i32 s8, s6, 0x10000
	v_add_f32_e32 v64, v64, v66
	s_nop 1
	v_mov_b32_e32 v65, v64
	s_nop 1
	v_permlane32_swap_b32_e32 v64, v65
	v_cmp_gt_u32_e32 vcc, 32, v137
	s_and_saveexec_b64 s[6:7], vcc
	v_add_f32_e32 v64, v64, v65
	v_lshl_add_u32 v65, v156, 2, s8
	ds_write_b32 v65, v64
	s_or_b64 exec, exec, s[6:7]
	s_waitcnt lgkmcnt(0)
	v_add_u32_e32 v73, s8, v136
	ds_read_b128 v[64:67], v73
	ds_read_b128 v[68:71], v73 offset:32
	ds_read_b128 v[74:77], v73 offset:64
	ds_read_b128 v[90:93], v73 offset:96
	s_lshl_b32 s6, s18, 14
	s_waitcnt lgkmcnt(3)
	v_rcp_f32_e32 v86, v64
	v_rcp_f32_e32 v84, v65
	v_rcp_f32_e32 v82, v66
	v_rcp_f32_e32 v78, v67
	s_waitcnt lgkmcnt(2)
	v_rcp_f32_e32 v68, v68
	v_rcp_f32_e32 v66, v69
	v_rcp_f32_e32 v64, v70
	v_rcp_f32_e32 v72, v71
	s_waitcnt lgkmcnt(1)
	v_rcp_f32_e32 v74, v74
	v_rcp_f32_e32 v70, v75
	v_rcp_f32_e32 v88, v76
	v_rcp_f32_e32 v104, v77
	s_waitcnt lgkmcnt(0)
	v_rcp_f32_e32 v102, v90
	v_rcp_f32_e32 v98, v91
	v_rcp_f32_e32 v80, v92
	v_rcp_f32_e32 v76, v93
	s_add_i32 s6, s6, 0
	v_lshlrev_b32_e32 v65, 11, v157
	v_lshlrev_b32_e32 v81, 2, v156
	s_cmp_lg_u32 s17, 1
	v_add3_u32 v77, s6, v65, v81
	s_barrier
	s_cbranch_scc1 .LBB0_343
	v_mul_f32_e32 v65, v0, v86
	v_mul_f32_e32 v67, v16, v86
	v_mul_f32_e32 v65, s11, v65
	v_mul_f32_e32 v67, s11, v67
	ds_write2_b32 v77, v65, v67 offset1:32
	v_mul_f32_e32 v65, v32, v86
	v_mul_f32_e32 v67, v48, v86
	v_mul_f32_e32 v65, s11, v65
	v_mul_f32_e32 v67, s11, v67
	ds_write2_b32 v77, v65, v67 offset0:64 offset1:96
	v_mul_f32_e32 v65, v1, v84
	v_mul_f32_e32 v67, v17, v84
	v_mul_f32_e32 v65, s11, v65
	v_mul_f32_e32 v67, s11, v67
	ds_write2_b32 v77, v65, v67 offset0:128 offset1:160
	v_mul_f32_e32 v65, v33, v84
	v_mul_f32_e32 v67, v49, v84
	v_mul_f32_e32 v65, s11, v65
	v_mul_f32_e32 v67, s11, v67
	ds_write2_b32 v77, v65, v67 offset0:192 offset1:224
	v_mul_f32_e32 v65, v2, v82
	v_mul_f32_e32 v67, v18, v82
	v_mul_f32_e32 v65, s11, v65
	v_mul_f32_e32 v67, s11, v67
	v_add_u32_e32 v69, 0x400, v77
	ds_write2_b32 v69, v65, v67 offset1:32
	v_mul_f32_e32 v65, v34, v82
	v_mul_f32_e32 v67, v50, v82
	v_mul_f32_e32 v65, s11, v65
	v_mul_f32_e32 v67, s11, v67
	ds_write2_b32 v69, v65, v67 offset0:64 offset1:96
	v_mul_f32_e32 v65, v3, v78
	v_mul_f32_e32 v67, v19, v78
	v_mul_f32_e32 v65, s11, v65
	v_mul_f32_e32 v67, s11, v67
	ds_write2_b32 v69, v65, v67 offset0:128 offset1:160
	v_mul_f32_e32 v65, v35, v78
	v_mul_f32_e32 v67, v51, v78
	v_mul_f32_e32 v65, s11, v65
	v_mul_f32_e32 v67, s11, v67
	ds_write2_b32 v69, v65, v67 offset0:192 offset1:224
	v_mul_f32_e32 v65, v4, v68
	v_mul_f32_e32 v67, v20, v68
	v_mul_f32_e32 v65, s11, v65
	v_mul_f32_e32 v67, s11, v67
	v_add_u32_e32 v69, 0x1000, v77
	ds_write2_b32 v69, v65, v67 offset1:32
	v_mul_f32_e32 v65, v36, v68
	v_mul_f32_e32 v67, v52, v68
	v_mul_f32_e32 v65, s11, v65
	v_mul_f32_e32 v67, s11, v67
	ds_write2_b32 v69, v65, v67 offset0:64 offset1:96
	v_mul_f32_e32 v65, v5, v66
	v_mul_f32_e32 v67, v21, v66
	v_mul_f32_e32 v65, s11, v65
	v_mul_f32_e32 v67, s11, v67
	ds_write2_b32 v69, v65, v67 offset0:128 offset1:160
	v_mul_f32_e32 v65, v37, v66
	v_mul_f32_e32 v67, v53, v66
	v_mul_f32_e32 v65, s11, v65
	v_mul_f32_e32 v67, s11, v67
	ds_write2_b32 v69, v65, v67 offset0:192 offset1:224
	v_mul_f32_e32 v65, v6, v64
	v_mul_f32_e32 v67, v22, v64
	v_mul_f32_e32 v65, s11, v65
	v_mul_f32_e32 v67, s11, v67
	v_add_u32_e32 v69, 0x1400, v77
	ds_write2_b32 v69, v65, v67 offset1:32
	v_mul_f32_e32 v65, v38, v64
	v_mul_f32_e32 v67, v54, v64
	v_mul_f32_e32 v65, s11, v65
	v_mul_f32_e32 v67, s11, v67
	ds_write2_b32 v69, v65, v67 offset0:64 offset1:96
	v_mul_f32_e32 v65, v7, v72
	v_mul_f32_e32 v67, v23, v72
	v_mul_f32_e32 v65, s11, v65
	v_mul_f32_e32 v67, s11, v67
	ds_write2_b32 v69, v65, v67 offset0:128 offset1:160
	v_mul_f32_e32 v65, v39, v72
	v_mul_f32_e32 v67, v55, v72
	v_mul_f32_e32 v65, s11, v65
	v_mul_f32_e32 v67, s11, v67
	ds_write2_b32 v69, v65, v67 offset0:192 offset1:224
	v_mul_f32_e32 v65, v8, v74
	v_mul_f32_e32 v67, v24, v74
	v_mul_f32_e32 v65, s11, v65
	v_mul_f32_e32 v67, s11, v67
	v_add_u32_e32 v69, 0x2000, v77
	ds_write2_b32 v69, v65, v67 offset1:32
	v_mul_f32_e32 v65, v40, v74
	v_mul_f32_e32 v67, v56, v74
	v_mul_f32_e32 v65, s11, v65
	v_mul_f32_e32 v67, s11, v67
	ds_write2_b32 v69, v65, v67 offset0:64 offset1:96
	v_mul_f32_e32 v65, v9, v70
	v_mul_f32_e32 v67, v25, v70
	v_mul_f32_e32 v65, s11, v65
	v_mul_f32_e32 v67, s11, v67
	ds_write2_b32 v69, v65, v67 offset0:128 offset1:160
	v_mul_f32_e32 v65, v41, v70
	v_mul_f32_e32 v67, v57, v70
	v_mul_f32_e32 v65, s11, v65
	v_mul_f32_e32 v67, s11, v67
	ds_write2_b32 v69, v65, v67 offset0:192 offset1:224
	v_mul_f32_e32 v65, v10, v88
	v_mul_f32_e32 v67, v26, v88
	v_mul_f32_e32 v65, s11, v65
	v_mul_f32_e32 v67, s11, v67
	v_add_u32_e32 v69, 0x2400, v77
	ds_write2_b32 v69, v65, v67 offset1:32
	v_mul_f32_e32 v65, v42, v88
	v_mul_f32_e32 v67, v58, v88
	v_mul_f32_e32 v65, s11, v65
	v_mul_f32_e32 v67, s11, v67
	ds_write2_b32 v69, v65, v67 offset0:64 offset1:96
	v_mul_f32_e32 v65, v11, v104
	v_mul_f32_e32 v67, v27, v104
	v_mul_f32_e32 v65, s11, v65
	v_mul_f32_e32 v67, s11, v67
	ds_write2_b32 v69, v65, v67 offset0:128 offset1:160
	v_mul_f32_e32 v65, v43, v104
	v_mul_f32_e32 v67, v59, v104
	v_mul_f32_e32 v65, s11, v65
	v_mul_f32_e32 v67, s11, v67
	ds_write2_b32 v69, v65, v67 offset0:192 offset1:224
	v_mul_f32_e32 v65, v12, v102
	v_mul_f32_e32 v67, v28, v102
	v_mul_f32_e32 v65, s11, v65
	v_mul_f32_e32 v67, s11, v67
	v_add_u32_e32 v69, 0x3000, v77
	ds_write2_b32 v69, v65, v67 offset1:32
	v_mul_f32_e32 v65, v44, v102
	v_mul_f32_e32 v67, v60, v102
	v_mul_f32_e32 v65, s11, v65
	v_mul_f32_e32 v67, s11, v67
	ds_write2_b32 v69, v65, v67 offset0:64 offset1:96
	v_mul_f32_e32 v65, v13, v98
	v_mul_f32_e32 v67, v29, v98
	v_mul_f32_e32 v65, s11, v65
	v_mul_f32_e32 v67, s11, v67
	ds_write2_b32 v69, v65, v67 offset0:128 offset1:160
	v_mul_f32_e32 v65, v45, v98
	v_mul_f32_e32 v67, v61, v98
	v_mul_f32_e32 v65, s11, v65
	v_mul_f32_e32 v67, s11, v67
	ds_write2_b32 v69, v65, v67 offset0:192 offset1:224
	v_mul_f32_e32 v65, v14, v80
	v_mul_f32_e32 v67, v30, v80
	v_mul_f32_e32 v65, s11, v65
	v_mul_f32_e32 v67, s11, v67
	v_add_u32_e32 v69, 0x3400, v77
	ds_write2_b32 v69, v65, v67 offset1:32
	v_mul_f32_e32 v65, v46, v80
	v_mul_f32_e32 v67, v62, v80
	v_mul_f32_e32 v65, s11, v65
	v_mul_f32_e32 v67, s11, v67
	ds_write2_b32 v69, v65, v67 offset0:64 offset1:96
	v_mul_f32_e32 v65, v15, v76
	v_mul_f32_e32 v67, v31, v76
	v_mul_f32_e32 v65, s11, v65
	v_mul_f32_e32 v67, s11, v67
	ds_write2_b32 v69, v65, v67 offset0:128 offset1:160
	v_mul_f32_e32 v65, v47, v76
	v_mul_f32_e32 v67, v63, v76
	v_mul_f32_e32 v65, s11, v65
	v_mul_f32_e32 v67, s11, v67
	ds_write2_b32 v69, v65, v67 offset0:192 offset1:224

; __global__ void __launch_bounds__(NTHREADS, 2) hymba_fwd(Args args) {
	.amdhsa_kernel _Z9hymba_fwd4Args
		.amdhsa_group_segment_fixed_size 0
		.amdhsa_private_segment_fixed_size 0
		.amdhsa_kernarg_size 496
		.amdhsa_user_sgpr_count 2
		.amdhsa_user_sgpr_dispatch_ptr 0
		.amdhsa_user_sgpr_queue_ptr 0
		.amdhsa_user_sgpr_kernarg_segment_ptr 1
		.amdhsa_user_sgpr_dispatch_id 0
		.amdhsa_user_sgpr_kernarg_preload_length 0
		.amdhsa_user_sgpr_kernarg_preload_offset 0
		.amdhsa_user_sgpr_private_segment_size 0
		.amdhsa_uses_dynamic_stack 0
		.amdhsa_enable_private_segment 0
		.amdhsa_system_sgpr_workgroup_id_x 1
		.amdhsa_system_sgpr_workgroup_id_y 0
		.amdhsa_system_sgpr_workgroup_id_z 0
		.amdhsa_system_sgpr_workgroup_info 0
		.amdhsa_system_vgpr_workitem_id 2
		.amdhsa_next_free_vgpr 256
		.amdhsa_next_free_sgpr 102
		.amdhsa_accum_offset 256
		.amdhsa_reserve_vcc 1
		.amdhsa_float_round_mode_32 0
		.amdhsa_float_round_mode_16_64 0
		.amdhsa_float_denorm_mode_32 3
		.amdhsa_float_denorm_mode_16_64 3
		.amdhsa_dx10_clamp 1
		.amdhsa_ieee_mode 1
		.amdhsa_fp16_overflow 0
		.amdhsa_tg_split 0
		.amdhsa_exception_fp_ieee_invalid_op 0
		.amdhsa_exception_fp_denorm_src 0
		.amdhsa_exception_fp_ieee_div_zero 0
		.amdhsa_exception_fp_ieee_overflow 0
		.amdhsa_exception_fp_ieee_underflow 0
		.amdhsa_exception_fp_ieee_inexact 0
		.amdhsa_exception_int_div_zero 0
	.end_amdhsa_kernel

; __global__ void __launch_bounds__(NTHREADS, 2) hymba_fwd(Args args) {
amdhsa.kernels:
  - .agpr_count:     0
    .args:
      - .offset:         0
        .size:           240
        .value_kind:     by_value
      - .offset:         240
        .size:           4
        .value_kind:     hidden_block_count_x
      - .offset:         244
        .size:           4
        .value_kind:     hidden_block_count_y
      - .offset:         248
        .size:           4
        .value_kind:     hidden_block_count_z
      - .offset:         252
        .size:           2
        .value_kind:     hidden_group_size_x
      - .offset:         254
        .size:           2
        .value_kind:     hidden_group_size_y
      - .offset:         256
        .size:           2
        .value_kind:     hidden_group_size_z
      - .offset:         258
        .size:           2
        .value_kind:     hidden_remainder_x
      - .offset:         260
        .size:           2
        .value_kind:     hidden_remainder_y
      - .offset:         262
        .size:           2
        .value_kind:     hidden_remainder_z
      - .offset:         280
        .size:           8
        .value_kind:     hidden_global_offset_x
      - .offset:         288
        .size:           8
        .value_kind:     hidden_global_offset_y
      - .offset:         296
        .size:           8
        .value_kind:     hidden_global_offset_z
      - .offset:         304
        .size:           2
        .value_kind:     hidden_grid_dims
      - .offset:         328
        .size:           8
        .value_kind:     hidden_multigrid_sync_arg
      - .offset:         360
        .size:           4
        .value_kind:     hidden_dynamic_lds_size
    .group_segment_fixed_size: 0
    .kernarg_segment_align: 8
    .kernarg_segment_size: 496
    .language:       OpenCL C
    .language_version:
      - 2
      - 0
    .max_flat_workgroup_size: 512
    .name:           _Z9hymba_fwd4Args
    .private_segment_fixed_size: 0
    .sgpr_count:     108
    .sgpr_spill_count: 118
    .symbol:         _Z9hymba_fwd4Args.kd
    .uniform_work_group_size: 1
    .uses_dynamic_stack: false
    .vgpr_count:     256
    .vgpr_spill_count: 0
    .wavefront_size: 64
